# v39: like v38 but the final product with the up projection is packed too (v_pk_mul_f32), clamps read the packed result directly
# baseline (speedup 1.0000x reference)
.Lpeel_exit_2:
	s_mov_b32 s98, 0x3b000000
	s_mov_b32 s99, 0xbcb8aa3b
	s_mov_b32 s100, 1.0
	v_pk_mul_f32 v[236:237], v[158:159], s[98:99] op_sel_hi:[1,0]
	v_pk_mul_f32 v[234:235], v[158:159], s[98:99] op_sel:[0,1] op_sel_hi:[1,1]
	v_exp_f32_e32 v234, v234
	v_exp_f32_e32 v235, v235
	s_nop 0
	v_pk_add_f32 v[234:235], v[234:235], s[100:101] op_sel_hi:[1,0]
	v_rcp_f32_e32 v234, v234
	v_rcp_f32_e32 v235, v235
	s_nop 0
	v_pk_mul_f32 v[236:237], v[236:237], v[234:235]
	v_pk_mul_f32 v[236:237], v[236:237], v[154:155]
	s_ashr_i32 s29, s28, 31
	s_ashr_i32 s27, s26, 31
	s_lshl_b64 s[10:11], s[28:29], 18
	s_lshl_b64 s[26:27], s[26:27], 15
	v_mov_b32_e32 v3, v195
	s_add_u32 s0, s6, s10
	v_med3_f32 v5, v236, s40, v190
	s_nop 15
	s_nop 15
	v_mov_b32_e32 v2, v196
	v_pk_mul_f32 v[238:239], v[160:161], s[98:99] op_sel_hi:[1,0]
	v_pk_mul_f32 v[234:235], v[160:161], s[98:99] op_sel:[0,1] op_sel_hi:[1,1]
	v_exp_f32_e32 v234, v234
	v_exp_f32_e32 v235, v235
	s_nop 0
	v_pk_add_f32 v[234:235], v[234:235], s[100:101] op_sel_hi:[1,0]
	v_rcp_f32_e32 v234, v234
	v_rcp_f32_e32 v235, v235
	s_nop 0
	v_pk_mul_f32 v[238:239], v[238:239], v[234:235]
	v_pk_mul_f32 v[238:239], v[238:239], v[156:157]
	v_add_u32_e32 v4, s49, v3
	s_addc_u32 s1, s7, s11
	s_add_u32 s10, s0, s26
	v_lshl_add_u32 v2, v2, 3, s50
	s_addc_u32 s11, s1, s27
	v_ashrrev_i32_e32 v3, 31, v2
	s_and_b64 vcc, exec, s[8:9]
	v_pk_mul_f32 v[240:241], v[150:151], s[98:99] op_sel_hi:[1,0]
	v_pk_mul_f32 v[234:235], v[150:151], s[98:99] op_sel:[0,1] op_sel_hi:[1,1]
	v_exp_f32_e32 v234, v234
	v_exp_f32_e32 v235, v235
	s_nop 0
	v_pk_add_f32 v[234:235], v[234:235], s[100:101] op_sel_hi:[1,0]
	v_rcp_f32_e32 v234, v234
	v_rcp_f32_e32 v235, v235
	s_nop 0
	v_pk_mul_f32 v[240:241], v[240:241], v[234:235]
	v_pk_mul_f32 v[240:241], v[240:241], v[146:147]
	v_mov_b32_e32 v174, v200
	v_mov_b32_e32 v172, v199
	v_mov_b32_e32 v170, v198
	v_mov_b32_e32 v168, v171
	s_mov_b32 s26, s24
	s_mov_b32 s28, s54
	s_mov_b64 s[30:31], s[12:13]
	v_pk_mul_f32 v[242:243], v[152:153], s[98:99] op_sel_hi:[1,0]
	v_pk_mul_f32 v[234:235], v[152:153], s[98:99] op_sel:[0,1] op_sel_hi:[1,1]
	v_exp_f32_e32 v234, v234
	v_exp_f32_e32 v235, v235
	s_nop 0
	v_pk_add_f32 v[234:235], v[234:235], s[100:101] op_sel_hi:[1,0]
	v_rcp_f32_e32 v234, v234
	v_rcp_f32_e32 v235, v235
	s_nop 0
	v_pk_mul_f32 v[242:243], v[242:243], v[234:235]
	v_pk_mul_f32 v[242:243], v[242:243], v[148:149]
	s_nop 0
	s_nop 0
	v_med3_f32 v13, v237, s40, v190
	v_mov_b32_e32 v6, v163
	v_cvt_pk_fp8_f32 v6, v5, v13
	v_med3_f32 v5, v238, s40, v190
	v_med3_f32 v7, v239, s40, v190
	v_med3_f32 v8, v241, s40, v190
	v_cvt_pk_fp8_f32 v6, v5, v7 op_sel:[0,0,1]
	v_med3_f32 v5, v240, s40, v190
	v_mov_b32_e32 v7, v163
	v_cvt_pk_fp8_f32 v7, v5, v8
	v_med3_f32 v5, v242, s40, v190
	v_med3_f32 v8, v243, s40, v190
	v_cvt_pk_fp8_f32 v7, v5, v8 op_sel:[0,0,1]
	v_ashrrev_i32_e32 v5, 31, v4
	v_lshlrev_b64 v[8:9], 7, v[4:5]
	v_lshl_add_u64 v[8:9], s[10:11], 0, v[8:9]
	v_lshl_add_u64 v[8:9], v[8:9], 0, v[2:3]
	v_pk_mul_f32 v[244:245], v[142:143], s[98:99] op_sel_hi:[1,0]
	v_pk_mul_f32 v[234:235], v[142:143], s[98:99] op_sel:[0,1] op_sel_hi:[1,1]
	v_exp_f32_e32 v234, v234
	v_exp_f32_e32 v235, v235
	s_nop 0
	v_pk_add_f32 v[234:235], v[234:235], s[100:101] op_sel_hi:[1,0]
	v_rcp_f32_e32 v234, v234
	v_rcp_f32_e32 v235, v235
	s_nop 0
	v_pk_mul_f32 v[244:245], v[244:245], v[234:235]
	v_pk_mul_f32 v[244:245], v[244:245], v[138:139]
	global_store_dwordx2 v[8:9], v[6:7], off
	s_nop 0
	s_nop 0
	v_med3_f32 v5, v244, s40, v190
	s_nop 0
	v_pk_mul_f32 v[246:247], v[144:145], s[98:99] op_sel_hi:[1,0]
	v_pk_mul_f32 v[234:235], v[144:145], s[98:99] op_sel:[0,1] op_sel_hi:[1,1]
	v_exp_f32_e32 v234, v234
	v_exp_f32_e32 v235, v235
	s_nop 0
	v_pk_add_f32 v[234:235], v[234:235], s[100:101] op_sel_hi:[1,0]
	v_rcp_f32_e32 v234, v234
	v_rcp_f32_e32 v235, v235
	s_nop 0
	v_pk_mul_f32 v[246:247], v[246:247], v[234:235]
	v_pk_mul_f32 v[246:247], v[246:247], v[140:141]
	v_med3_f32 v7, v245, s40, v190
	s_nop 0
	s_nop 0
	s_nop 0
	v_pk_mul_f32 v[248:249], v[134:135], s[98:99] op_sel_hi:[1,0]
	v_pk_mul_f32 v[234:235], v[134:135], s[98:99] op_sel:[0,1] op_sel_hi:[1,1]
	v_exp_f32_e32 v234, v234
	v_exp_f32_e32 v235, v235
	s_nop 0
	v_pk_add_f32 v[234:235], v[234:235], s[100:101] op_sel_hi:[1,0]
	v_rcp_f32_e32 v234, v234
	v_rcp_f32_e32 v235, v235
	s_nop 0
	v_pk_mul_f32 v[248:249], v[248:249], v[234:235]
	v_pk_mul_f32 v[248:249], v[248:249], v[130:131]
	s_nop 0
	s_nop 0
	s_nop 0
	s_nop 0
	v_pk_mul_f32 v[250:251], v[136:137], s[98:99] op_sel_hi:[1,0]
	v_pk_mul_f32 v[234:235], v[136:137], s[98:99] op_sel:[0,1] op_sel_hi:[1,1]
	v_exp_f32_e32 v234, v234
	v_exp_f32_e32 v235, v235
	s_nop 0
	v_pk_add_f32 v[234:235], v[234:235], s[100:101] op_sel_hi:[1,0]
	v_rcp_f32_e32 v234, v234
	v_rcp_f32_e32 v235, v235
	s_nop 0
	v_pk_mul_f32 v[250:251], v[250:251], v[234:235]
	v_pk_mul_f32 v[250:251], v[250:251], v[132:133]
	s_nop 0
	s_nop 0
	s_nop 0
	s_nop 0
	v_mov_b32_e32 v8, v163
	v_cvt_pk_fp8_f32 v8, v5, v7
	v_med3_f32 v5, v246, s40, v190
	v_med3_f32 v7, v247, s40, v190
	v_mov_b32_e32 v9, v163
	v_cvt_pk_fp8_f32 v8, v5, v7 op_sel:[0,0,1]
	v_med3_f32 v5, v248, s40, v190
	v_med3_f32 v7, v249, s40, v190
	v_cvt_pk_fp8_f32 v9, v5, v7
	v_add_u32_e32 v6, 16, v4
	v_med3_f32 v5, v250, s40, v190
	v_med3_f32 v7, v251, s40, v190
	v_cvt_pk_fp8_f32 v9, v5, v7 op_sel:[0,0,1]
	v_ashrrev_i32_e32 v7, 31, v6
	v_lshlrev_b64 v[6:7], 7, v[6:7]
	v_lshl_add_u64 v[6:7], s[10:11], 0, v[6:7]
	v_lshl_add_u64 v[6:7], v[6:7], 0, v[2:3]
	v_pk_mul_f32 v[236:237], v[126:127], s[98:99] op_sel_hi:[1,0]
	v_pk_mul_f32 v[234:235], v[126:127], s[98:99] op_sel:[0,1] op_sel_hi:[1,1]
	v_exp_f32_e32 v234, v234
	v_exp_f32_e32 v235, v235
	s_nop 0
	v_pk_add_f32 v[234:235], v[234:235], s[100:101] op_sel_hi:[1,0]
	v_rcp_f32_e32 v234, v234
	v_rcp_f32_e32 v235, v235
	s_nop 0
	v_pk_mul_f32 v[236:237], v[236:237], v[234:235]
	v_pk_mul_f32 v[236:237], v[236:237], v[122:123]
	global_store_dwordx2 v[6:7], v[8:9], off
	s_nop 0
	s_nop 0
	v_med3_f32 v5, v236, s40, v190
	s_nop 0
	v_pk_mul_f32 v[238:239], v[128:129], s[98:99] op_sel_hi:[1,0]
	v_pk_mul_f32 v[234:235], v[128:129], s[98:99] op_sel:[0,1] op_sel_hi:[1,1]
	v_exp_f32_e32 v234, v234
	v_exp_f32_e32 v235, v235
	s_nop 0
	v_pk_add_f32 v[234:235], v[234:235], s[100:101] op_sel_hi:[1,0]
	v_rcp_f32_e32 v234, v234
	v_rcp_f32_e32 v235, v235
	s_nop 0
	v_pk_mul_f32 v[238:239], v[238:239], v[234:235]
	v_pk_mul_f32 v[238:239], v[238:239], v[124:125]
	v_med3_f32 v7, v237, s40, v190
	s_nop 0
	s_nop 0
	s_nop 0
	v_pk_mul_f32 v[240:241], v[118:119], s[98:99] op_sel_hi:[1,0]
	v_pk_mul_f32 v[234:235], v[118:119], s[98:99] op_sel:[0,1] op_sel_hi:[1,1]
	v_exp_f32_e32 v234, v234
	v_exp_f32_e32 v235, v235
	s_nop 0
	v_pk_add_f32 v[234:235], v[234:235], s[100:101] op_sel_hi:[1,0]
	v_rcp_f32_e32 v234, v234
	v_rcp_f32_e32 v235, v235
	s_nop 0
	v_pk_mul_f32 v[240:241], v[240:241], v[234:235]
	v_pk_mul_f32 v[240:241], v[240:241], v[114:115]
	s_nop 0
	s_nop 0
	s_nop 0
	s_nop 0
	v_pk_mul_f32 v[242:243], v[120:121], s[98:99] op_sel_hi:[1,0]
	v_pk_mul_f32 v[234:235], v[120:121], s[98:99] op_sel:[0,1] op_sel_hi:[1,1]
	v_exp_f32_e32 v234, v234
	v_exp_f32_e32 v235, v235
	s_nop 0
	v_pk_add_f32 v[234:235], v[234:235], s[100:101] op_sel_hi:[1,0]
	v_rcp_f32_e32 v234, v234
	v_rcp_f32_e32 v235, v235
	s_nop 0
	v_pk_mul_f32 v[242:243], v[242:243], v[234:235]
	v_pk_mul_f32 v[242:243], v[242:243], v[116:117]
	s_nop 0
	s_nop 0
	s_nop 0
	s_nop 0
	v_mov_b32_e32 v8, v163
	v_cvt_pk_fp8_f32 v8, v5, v7
	v_med3_f32 v5, v238, s40, v190
	v_med3_f32 v7, v239, s40, v190
	v_mov_b32_e32 v9, v163
	v_cvt_pk_fp8_f32 v8, v5, v7 op_sel:[0,0,1]
	v_med3_f32 v5, v240, s40, v190
	v_med3_f32 v7, v241, s40, v190
	v_cvt_pk_fp8_f32 v9, v5, v7
	v_add_u32_e32 v6, 32, v4
	v_med3_f32 v5, v242, s40, v190
	v_med3_f32 v7, v243, s40, v190
	v_cvt_pk_fp8_f32 v9, v5, v7 op_sel:[0,0,1]
	v_ashrrev_i32_e32 v7, 31, v6
	v_lshlrev_b64 v[6:7], 7, v[6:7]
	v_lshl_add_u64 v[6:7], s[10:11], 0, v[6:7]
	v_lshl_add_u64 v[6:7], v[6:7], 0, v[2:3]
	v_pk_mul_f32 v[244:245], v[110:111], s[98:99] op_sel_hi:[1,0]
	v_pk_mul_f32 v[234:235], v[110:111], s[98:99] op_sel:[0,1] op_sel_hi:[1,1]
	v_exp_f32_e32 v234, v234
	v_exp_f32_e32 v235, v235
	s_nop 0
	v_pk_add_f32 v[234:235], v[234:235], s[100:101] op_sel_hi:[1,0]
	v_rcp_f32_e32 v234, v234
	v_rcp_f32_e32 v235, v235
	s_nop 0
	v_pk_mul_f32 v[244:245], v[244:245], v[234:235]
	v_pk_mul_f32 v[244:245], v[244:245], v[106:107]
	global_store_dwordx2 v[6:7], v[8:9], off
	s_nop 0
	s_nop 0
	v_med3_f32 v5, v244, s40, v190
	s_nop 0
	v_pk_mul_f32 v[246:247], v[112:113], s[98:99] op_sel_hi:[1,0]
	v_pk_mul_f32 v[234:235], v[112:113], s[98:99] op_sel:[0,1] op_sel_hi:[1,1]
	v_exp_f32_e32 v234, v234
	v_exp_f32_e32 v235, v235
	s_nop 0
	v_pk_add_f32 v[234:235], v[234:235], s[100:101] op_sel_hi:[1,0]
	v_rcp_f32_e32 v234, v234
	v_rcp_f32_e32 v235, v235
	s_nop 0
	v_pk_mul_f32 v[246:247], v[246:247], v[234:235]
	v_pk_mul_f32 v[246:247], v[246:247], v[108:109]
	v_med3_f32 v7, v245, s40, v190
	s_nop 0
	s_nop 0
	s_nop 0
	v_pk_mul_f32 v[248:249], v[102:103], s[98:99] op_sel_hi:[1,0]
	v_pk_mul_f32 v[234:235], v[102:103], s[98:99] op_sel:[0,1] op_sel_hi:[1,1]
	v_exp_f32_e32 v234, v234
	v_exp_f32_e32 v235, v235
	s_nop 0
	v_pk_add_f32 v[234:235], v[234:235], s[100:101] op_sel_hi:[1,0]
	v_rcp_f32_e32 v234, v234
	v_rcp_f32_e32 v235, v235
	s_nop 0
	v_pk_mul_f32 v[248:249], v[248:249], v[234:235]
	v_pk_mul_f32 v[248:249], v[248:249], v[98:99]
	s_nop 0
	s_nop 0
	s_nop 0
	s_nop 0
	v_pk_mul_f32 v[250:251], v[104:105], s[98:99] op_sel_hi:[1,0]
	v_pk_mul_f32 v[234:235], v[104:105], s[98:99] op_sel:[0,1] op_sel_hi:[1,1]
	v_exp_f32_e32 v234, v234
	v_exp_f32_e32 v235, v235
	s_nop 0
	v_pk_add_f32 v[234:235], v[234:235], s[100:101] op_sel_hi:[1,0]
	v_rcp_f32_e32 v234, v234
	v_rcp_f32_e32 v235, v235
	s_nop 0
	v_pk_mul_f32 v[250:251], v[250:251], v[234:235]
	v_pk_mul_f32 v[250:251], v[250:251], v[100:101]
	s_nop 0
	s_nop 0
	s_nop 0
	s_nop 0
	v_mov_b32_e32 v8, v163
	v_cvt_pk_fp8_f32 v8, v5, v7
	v_med3_f32 v5, v246, s40, v190
	v_med3_f32 v7, v247, s40, v190
	v_mov_b32_e32 v9, v163
	v_cvt_pk_fp8_f32 v8, v5, v7 op_sel:[0,0,1]
	v_med3_f32 v5, v248, s40, v190
	v_med3_f32 v7, v249, s40, v190
	v_cvt_pk_fp8_f32 v9, v5, v7
	v_add_u32_e32 v6, 48, v4
	v_med3_f32 v5, v250, s40, v190
	v_med3_f32 v7, v251, s40, v190
	v_cvt_pk_fp8_f32 v9, v5, v7 op_sel:[0,0,1]
	v_ashrrev_i32_e32 v7, 31, v6
	v_lshlrev_b64 v[6:7], 7, v[6:7]
	v_lshl_add_u64 v[6:7], s[10:11], 0, v[6:7]
	v_lshl_add_u64 v[6:7], v[6:7], 0, v[2:3]
	v_pk_mul_f32 v[236:237], v[94:95], s[98:99] op_sel_hi:[1,0]
	v_pk_mul_f32 v[234:235], v[94:95], s[98:99] op_sel:[0,1] op_sel_hi:[1,1]
	v_exp_f32_e32 v234, v234
	v_exp_f32_e32 v235, v235
	s_nop 0
	v_pk_add_f32 v[234:235], v[234:235], s[100:101] op_sel_hi:[1,0]
	v_rcp_f32_e32 v234, v234
	v_rcp_f32_e32 v235, v235
	s_nop 0
	v_pk_mul_f32 v[236:237], v[236:237], v[234:235]
	v_pk_mul_f32 v[236:237], v[236:237], v[90:91]
	global_store_dwordx2 v[6:7], v[8:9], off
	v_add_u32_e32 v6, 0x80, v4
	s_nop 0
	v_med3_f32 v5, v236, s40, v190
	s_nop 0
	v_pk_mul_f32 v[238:239], v[96:97], s[98:99] op_sel_hi:[1,0]
	v_pk_mul_f32 v[234:235], v[96:97], s[98:99] op_sel:[0,1] op_sel_hi:[1,1]
	v_exp_f32_e32 v234, v234
	v_exp_f32_e32 v235, v235
	s_nop 0
	v_pk_add_f32 v[234:235], v[234:235], s[100:101] op_sel_hi:[1,0]
	v_rcp_f32_e32 v234, v234
	v_rcp_f32_e32 v235, v235
	s_nop 0
	v_pk_mul_f32 v[238:239], v[238:239], v[234:235]
	v_pk_mul_f32 v[238:239], v[238:239], v[92:93]
	v_med3_f32 v7, v237, s40, v190
	s_nop 0
	s_nop 0
	s_nop 0
	v_pk_mul_f32 v[240:241], v[86:87], s[98:99] op_sel_hi:[1,0]
	v_pk_mul_f32 v[234:235], v[86:87], s[98:99] op_sel:[0,1] op_sel_hi:[1,1]
	v_exp_f32_e32 v234, v234
	v_exp_f32_e32 v235, v235
	s_nop 0
	v_pk_add_f32 v[234:235], v[234:235], s[100:101] op_sel_hi:[1,0]
	v_rcp_f32_e32 v234, v234
	v_rcp_f32_e32 v235, v235
	s_nop 0
	v_pk_mul_f32 v[240:241], v[240:241], v[234:235]
	v_pk_mul_f32 v[240:241], v[240:241], v[82:83]
	s_nop 0
	s_nop 0
	s_nop 0
	s_nop 0
	v_pk_mul_f32 v[242:243], v[88:89], s[98:99] op_sel_hi:[1,0]
	v_pk_mul_f32 v[234:235], v[88:89], s[98:99] op_sel:[0,1] op_sel_hi:[1,1]
	v_exp_f32_e32 v234, v234
	v_exp_f32_e32 v235, v235
	s_nop 0
	v_pk_add_f32 v[234:235], v[234:235], s[100:101] op_sel_hi:[1,0]
	v_rcp_f32_e32 v234, v234
	v_rcp_f32_e32 v235, v235
	s_nop 0
	v_pk_mul_f32 v[242:243], v[242:243], v[234:235]
	v_pk_mul_f32 v[242:243], v[242:243], v[84:85]
	s_nop 0
	s_nop 0
	s_nop 0
	s_nop 0
	v_mov_b32_e32 v8, v163
	v_cvt_pk_fp8_f32 v8, v5, v7
	v_med3_f32 v5, v238, s40, v190
	v_med3_f32 v7, v239, s40, v190
	v_mov_b32_e32 v9, v163
	v_cvt_pk_fp8_f32 v8, v5, v7 op_sel:[0,0,1]
	v_med3_f32 v5, v240, s40, v190
	v_med3_f32 v7, v241, s40, v190
	v_cvt_pk_fp8_f32 v9, v5, v7
	v_med3_f32 v5, v242, s40, v190
	v_med3_f32 v7, v243, s40, v190
	v_cvt_pk_fp8_f32 v9, v5, v7 op_sel:[0,0,1]
	v_ashrrev_i32_e32 v7, 31, v6
	v_lshlrev_b64 v[6:7], 7, v[6:7]
	v_lshl_add_u64 v[6:7], s[10:11], 0, v[6:7]
	v_lshl_add_u64 v[6:7], v[6:7], 0, v[2:3]
	v_pk_mul_f32 v[244:245], v[78:79], s[98:99] op_sel_hi:[1,0]
	v_pk_mul_f32 v[234:235], v[78:79], s[98:99] op_sel:[0,1] op_sel_hi:[1,1]
	v_exp_f32_e32 v234, v234
	v_exp_f32_e32 v235, v235
	s_nop 0
	v_pk_add_f32 v[234:235], v[234:235], s[100:101] op_sel_hi:[1,0]
	v_rcp_f32_e32 v234, v234
	v_rcp_f32_e32 v235, v235
	s_nop 0
	v_pk_mul_f32 v[244:245], v[244:245], v[234:235]
	v_pk_mul_f32 v[244:245], v[244:245], v[74:75]
	global_store_dwordx2 v[6:7], v[8:9], off
	s_nop 0
	s_nop 0
	v_med3_f32 v5, v244, s40, v190
	s_nop 0
	v_pk_mul_f32 v[246:247], v[80:81], s[98:99] op_sel_hi:[1,0]
	v_pk_mul_f32 v[234:235], v[80:81], s[98:99] op_sel:[0,1] op_sel_hi:[1,1]
	v_exp_f32_e32 v234, v234
	v_exp_f32_e32 v235, v235
	s_nop 0
	v_pk_add_f32 v[234:235], v[234:235], s[100:101] op_sel_hi:[1,0]
	v_rcp_f32_e32 v234, v234
	v_rcp_f32_e32 v235, v235
	s_nop 0
	v_pk_mul_f32 v[246:247], v[246:247], v[234:235]
	v_pk_mul_f32 v[246:247], v[246:247], v[76:77]
	v_med3_f32 v7, v245, s40, v190
	s_nop 0
	s_nop 0
	s_nop 0
	v_pk_mul_f32 v[248:249], v[70:71], s[98:99] op_sel_hi:[1,0]
	v_pk_mul_f32 v[234:235], v[70:71], s[98:99] op_sel:[0,1] op_sel_hi:[1,1]
	v_exp_f32_e32 v234, v234
	v_exp_f32_e32 v235, v235
	s_nop 0
	v_pk_add_f32 v[234:235], v[234:235], s[100:101] op_sel_hi:[1,0]
	v_rcp_f32_e32 v234, v234
	v_rcp_f32_e32 v235, v235
	s_nop 0
	v_pk_mul_f32 v[248:249], v[248:249], v[234:235]
	v_pk_mul_f32 v[248:249], v[248:249], v[66:67]
	s_nop 0
	s_nop 0
	s_nop 0
	s_nop 0
	v_pk_mul_f32 v[250:251], v[72:73], s[98:99] op_sel_hi:[1,0]
	v_pk_mul_f32 v[234:235], v[72:73], s[98:99] op_sel:[0,1] op_sel_hi:[1,1]
	v_exp_f32_e32 v234, v234
	v_exp_f32_e32 v235, v235
	s_nop 0
	v_pk_add_f32 v[234:235], v[234:235], s[100:101] op_sel_hi:[1,0]
	v_rcp_f32_e32 v234, v234
	v_rcp_f32_e32 v235, v235
	s_nop 0
	v_pk_mul_f32 v[250:251], v[250:251], v[234:235]
	v_pk_mul_f32 v[250:251], v[250:251], v[68:69]
	s_nop 0
	s_nop 0
	s_nop 0
	s_nop 0
	v_mov_b32_e32 v8, v163
	v_cvt_pk_fp8_f32 v8, v5, v7
	v_med3_f32 v5, v246, s40, v190
	v_med3_f32 v7, v247, s40, v190
	v_mov_b32_e32 v9, v163
	v_cvt_pk_fp8_f32 v8, v5, v7 op_sel:[0,0,1]
	v_med3_f32 v5, v248, s40, v190
	v_med3_f32 v7, v249, s40, v190
	v_cvt_pk_fp8_f32 v9, v5, v7
	v_add_u32_e32 v6, 0x90, v4
	v_med3_f32 v5, v250, s40, v190
	v_med3_f32 v7, v251, s40, v190
	v_cvt_pk_fp8_f32 v9, v5, v7 op_sel:[0,0,1]
	v_ashrrev_i32_e32 v7, 31, v6
	v_lshlrev_b64 v[6:7], 7, v[6:7]
	v_lshl_add_u64 v[6:7], s[10:11], 0, v[6:7]
	v_lshl_add_u64 v[6:7], v[6:7], 0, v[2:3]
	v_pk_mul_f32 v[236:237], v[62:63], s[98:99] op_sel_hi:[1,0]
	v_pk_mul_f32 v[234:235], v[62:63], s[98:99] op_sel:[0,1] op_sel_hi:[1,1]
	v_exp_f32_e32 v234, v234
	v_exp_f32_e32 v235, v235
	s_nop 0
	v_pk_add_f32 v[234:235], v[234:235], s[100:101] op_sel_hi:[1,0]
	v_rcp_f32_e32 v234, v234
	v_rcp_f32_e32 v235, v235
	s_nop 0
	v_pk_mul_f32 v[236:237], v[236:237], v[234:235]
	v_pk_mul_f32 v[236:237], v[236:237], v[58:59]
	global_store_dwordx2 v[6:7], v[8:9], off
	s_nop 0
	s_nop 0
	v_med3_f32 v5, v236, s40, v190
	s_nop 0
	v_pk_mul_f32 v[238:239], v[64:65], s[98:99] op_sel_hi:[1,0]
	v_pk_mul_f32 v[234:235], v[64:65], s[98:99] op_sel:[0,1] op_sel_hi:[1,1]
	v_exp_f32_e32 v234, v234
	v_exp_f32_e32 v235, v235
	s_nop 0
	v_pk_add_f32 v[234:235], v[234:235], s[100:101] op_sel_hi:[1,0]
	v_rcp_f32_e32 v234, v234
	v_rcp_f32_e32 v235, v235
	s_nop 0
	v_pk_mul_f32 v[238:239], v[238:239], v[234:235]
	v_pk_mul_f32 v[238:239], v[238:239], v[60:61]
	v_med3_f32 v7, v237, s40, v190
	s_nop 0
	s_nop 0
	s_nop 0
	v_pk_mul_f32 v[240:241], v[54:55], s[98:99] op_sel_hi:[1,0]
	v_pk_mul_f32 v[234:235], v[54:55], s[98:99] op_sel:[0,1] op_sel_hi:[1,1]
	v_exp_f32_e32 v234, v234
	v_exp_f32_e32 v235, v235
	s_nop 0
	v_pk_add_f32 v[234:235], v[234:235], s[100:101] op_sel_hi:[1,0]
	v_rcp_f32_e32 v234, v234
	v_rcp_f32_e32 v235, v235
	s_nop 0
	v_pk_mul_f32 v[240:241], v[240:241], v[234:235]
	v_pk_mul_f32 v[240:241], v[240:241], v[50:51]
	s_nop 0
	s_nop 0
	s_nop 0
	s_nop 0
	v_pk_mul_f32 v[242:243], v[56:57], s[98:99] op_sel_hi:[1,0]
	v_pk_mul_f32 v[234:235], v[56:57], s[98:99] op_sel:[0,1] op_sel_hi:[1,1]
	v_exp_f32_e32 v234, v234
	v_exp_f32_e32 v235, v235
	s_nop 0
	v_pk_add_f32 v[234:235], v[234:235], s[100:101] op_sel_hi:[1,0]
	v_rcp_f32_e32 v234, v234
	v_rcp_f32_e32 v235, v235
	s_nop 0
	v_pk_mul_f32 v[242:243], v[242:243], v[234:235]
	v_pk_mul_f32 v[242:243], v[242:243], v[52:53]
	s_nop 0
	s_nop 0
	s_nop 0
	s_nop 0
	v_mov_b32_e32 v8, v163
	v_cvt_pk_fp8_f32 v8, v5, v7
	v_med3_f32 v5, v238, s40, v190
	v_med3_f32 v7, v239, s40, v190
	v_mov_b32_e32 v9, v163
	v_cvt_pk_fp8_f32 v8, v5, v7 op_sel:[0,0,1]
	v_med3_f32 v5, v240, s40, v190
	v_med3_f32 v7, v241, s40, v190
	v_cvt_pk_fp8_f32 v9, v5, v7
	v_add_u32_e32 v6, 0xa0, v4
	v_med3_f32 v5, v242, s40, v190
	v_med3_f32 v7, v243, s40, v190
	v_cvt_pk_fp8_f32 v9, v5, v7 op_sel:[0,0,1]
	v_ashrrev_i32_e32 v7, 31, v6
	v_lshlrev_b64 v[6:7], 7, v[6:7]
	v_lshl_add_u64 v[6:7], s[10:11], 0, v[6:7]
	v_lshl_add_u64 v[6:7], v[6:7], 0, v[2:3]
	v_pk_mul_f32 v[244:245], v[46:47], s[98:99] op_sel_hi:[1,0]
	v_pk_mul_f32 v[234:235], v[46:47], s[98:99] op_sel:[0,1] op_sel_hi:[1,1]
	v_exp_f32_e32 v234, v234
	v_exp_f32_e32 v235, v235
	s_nop 0
	v_pk_add_f32 v[234:235], v[234:235], s[100:101] op_sel_hi:[1,0]
	v_rcp_f32_e32 v234, v234
	v_rcp_f32_e32 v235, v235
	s_nop 0
	v_pk_mul_f32 v[244:245], v[244:245], v[234:235]
	v_pk_mul_f32 v[244:245], v[244:245], v[42:43]
	global_store_dwordx2 v[6:7], v[8:9], off
	v_add_u32_e32 v4, 0xb0, v4
	s_nop 0
	v_med3_f32 v5, v244, s40, v190
	s_nop 0
	v_pk_mul_f32 v[246:247], v[48:49], s[98:99] op_sel_hi:[1,0]
	v_pk_mul_f32 v[234:235], v[48:49], s[98:99] op_sel:[0,1] op_sel_hi:[1,1]
	v_exp_f32_e32 v234, v234
	v_exp_f32_e32 v235, v235
	s_nop 0
	v_pk_add_f32 v[234:235], v[234:235], s[100:101] op_sel_hi:[1,0]
	v_rcp_f32_e32 v234, v234
	v_rcp_f32_e32 v235, v235
	s_nop 0
	v_pk_mul_f32 v[246:247], v[246:247], v[234:235]
	v_pk_mul_f32 v[246:247], v[246:247], v[44:45]
	s_nop 0
	s_nop 0
	v_pk_mul_f32 v[248:249], v[38:39], s[98:99] op_sel_hi:[1,0]
	v_pk_mul_f32 v[234:235], v[38:39], s[98:99] op_sel:[0,1] op_sel_hi:[1,1]
	v_exp_f32_e32 v234, v234
	v_exp_f32_e32 v235, v235
	s_nop 0
	v_pk_add_f32 v[234:235], v[234:235], s[100:101] op_sel_hi:[1,0]
	v_rcp_f32_e32 v234, v234
	v_rcp_f32_e32 v235, v235
	s_nop 0
	v_pk_mul_f32 v[248:249], v[248:249], v[234:235]
	v_pk_mul_f32 v[248:249], v[248:249], v[34:35]
	s_nop 0
	s_nop 0
	v_pk_mul_f32 v[250:251], v[40:41], s[98:99] op_sel_hi:[1,0]
	v_pk_mul_f32 v[234:235], v[40:41], s[98:99] op_sel:[0,1] op_sel_hi:[1,1]
	v_exp_f32_e32 v234, v234
	v_exp_f32_e32 v235, v235
	s_nop 0
	v_pk_add_f32 v[234:235], v[234:235], s[100:101] op_sel_hi:[1,0]
	v_rcp_f32_e32 v234, v234
	v_rcp_f32_e32 v235, v235
	s_nop 0
	v_pk_mul_f32 v[250:251], v[250:251], v[234:235]
	v_pk_mul_f32 v[250:251], v[250:251], v[36:37]
	s_nop 0
	s_nop 0
	v_med3_f32 v13, v245, s40, v190
	v_mov_b32_e32 v6, v163
	v_cvt_pk_fp8_f32 v6, v5, v13
	v_med3_f32 v5, v246, s40, v190
	v_med3_f32 v7, v247, s40, v190
	v_med3_f32 v8, v249, s40, v190
	v_cvt_pk_fp8_f32 v6, v5, v7 op_sel:[0,0,1]
	v_med3_f32 v5, v248, s40, v190
	v_mov_b32_e32 v7, v163
	v_cvt_pk_fp8_f32 v7, v5, v8
	v_med3_f32 v5, v250, s40, v190
	v_med3_f32 v8, v251, s40, v190
	v_cvt_pk_fp8_f32 v7, v5, v8 op_sel:[0,0,1]
	v_ashrrev_i32_e32 v5, 31, v4
	v_lshlrev_b64 v[4:5], 7, v[4:5]
	v_lshl_add_u64 v[4:5], s[10:11], 0, v[4:5]
	v_lshl_add_u64 v[2:3], v[4:5], 0, v[2:3]
	global_store_dwordx2 v[2:3], v[6:7], off
	s_cbranch_vccz .LBB0_677
	s_waitcnt vmcnt(0)
	s_cmpk_gt_u32 s42, 0xff
	s_cbranch_scc1 .LBB0_623
	s_barrier
	s_branch .LBB0_623

.Lpeel_exit_6:
	s_mov_b32 s98, 0x3b000000
	s_mov_b32 s99, 0xbcb8aa3b
	s_mov_b32 s100, 1.0
	v_pk_mul_f32 v[236:237], v[158:159], s[98:99] op_sel_hi:[1,0]
	v_pk_mul_f32 v[234:235], v[158:159], s[98:99] op_sel:[0,1] op_sel_hi:[1,1]
	v_exp_f32_e32 v234, v234
	v_exp_f32_e32 v235, v235
	s_nop 0
	v_pk_add_f32 v[234:235], v[234:235], s[100:101] op_sel_hi:[1,0]
	v_rcp_f32_e32 v234, v234
	v_rcp_f32_e32 v235, v235
	s_nop 0
	v_pk_mul_f32 v[236:237], v[236:237], v[234:235]
	v_pk_mul_f32 v[236:237], v[236:237], v[154:155]
	s_ashr_i32 s31, s30, 31
	s_ashr_i32 s29, s28, 31
	s_lshl_b64 s[12:13], s[30:31], 18
	s_lshl_b64 s[28:29], s[28:29], 15
	v_mov_b32_e32 v3, v195
	s_add_u32 s0, s6, s12
	v_med3_f32 v5, v236, s40, v190
	s_nop 15
	s_nop 15
	v_mov_b32_e32 v2, v196
	v_pk_mul_f32 v[238:239], v[160:161], s[98:99] op_sel_hi:[1,0]
	v_pk_mul_f32 v[234:235], v[160:161], s[98:99] op_sel:[0,1] op_sel_hi:[1,1]
	v_exp_f32_e32 v234, v234
	v_exp_f32_e32 v235, v235
	s_nop 0
	v_pk_add_f32 v[234:235], v[234:235], s[100:101] op_sel_hi:[1,0]
	v_rcp_f32_e32 v234, v234
	v_rcp_f32_e32 v235, v235
	s_nop 0
	v_pk_mul_f32 v[238:239], v[238:239], v[234:235]
	v_pk_mul_f32 v[238:239], v[238:239], v[156:157]
	v_add_u32_e32 v4, s49, v3
	s_addc_u32 s1, s7, s13
	s_add_u32 s12, s0, s28
	v_lshl_add_u32 v2, v2, 3, s50
	s_addc_u32 s13, s1, s29
	v_ashrrev_i32_e32 v3, 31, v2
	s_and_b64 vcc, exec, s[8:9]
	v_pk_mul_f32 v[240:241], v[150:151], s[98:99] op_sel_hi:[1,0]
	v_pk_mul_f32 v[234:235], v[150:151], s[98:99] op_sel:[0,1] op_sel_hi:[1,1]
	v_exp_f32_e32 v234, v234
	v_exp_f32_e32 v235, v235
	s_nop 0
	v_pk_add_f32 v[234:235], v[234:235], s[100:101] op_sel_hi:[1,0]
	v_rcp_f32_e32 v234, v234
	v_rcp_f32_e32 v235, v235
	s_nop 0
	v_pk_mul_f32 v[240:241], v[240:241], v[234:235]
	v_pk_mul_f32 v[240:241], v[240:241], v[146:147]
	v_mov_b32_e32 v174, v200
	v_mov_b32_e32 v172, v199
	v_mov_b32_e32 v170, v198
	v_mov_b32_e32 v168, v171
	s_mov_b32 s28, s26
	s_mov_b32 s30, s54
	s_mov_b64 s[34:35], s[14:15]
	v_pk_mul_f32 v[242:243], v[152:153], s[98:99] op_sel_hi:[1,0]
	v_pk_mul_f32 v[234:235], v[152:153], s[98:99] op_sel:[0,1] op_sel_hi:[1,1]
	v_exp_f32_e32 v234, v234
	v_exp_f32_e32 v235, v235
	s_nop 0
	v_pk_add_f32 v[234:235], v[234:235], s[100:101] op_sel_hi:[1,0]
	v_rcp_f32_e32 v234, v234
	v_rcp_f32_e32 v235, v235
	s_nop 0
	v_pk_mul_f32 v[242:243], v[242:243], v[234:235]
	v_pk_mul_f32 v[242:243], v[242:243], v[148:149]
	s_nop 0
	s_nop 0
	v_med3_f32 v13, v237, s40, v190
	v_mov_b32_e32 v6, v163
	v_cvt_pk_fp8_f32 v6, v5, v13
	v_med3_f32 v5, v238, s40, v190
	v_med3_f32 v7, v239, s40, v190
	v_med3_f32 v8, v241, s40, v190
	v_cvt_pk_fp8_f32 v6, v5, v7 op_sel:[0,0,1]
	v_med3_f32 v5, v240, s40, v190
	v_mov_b32_e32 v7, v163
	v_cvt_pk_fp8_f32 v7, v5, v8
	v_med3_f32 v5, v242, s40, v190
	v_med3_f32 v8, v243, s40, v190
	v_cvt_pk_fp8_f32 v7, v5, v8 op_sel:[0,0,1]
	v_ashrrev_i32_e32 v5, 31, v4
	v_lshlrev_b64 v[8:9], 7, v[4:5]
	v_lshl_add_u64 v[8:9], s[12:13], 0, v[8:9]
	v_lshl_add_u64 v[8:9], v[8:9], 0, v[2:3]
	v_pk_mul_f32 v[244:245], v[142:143], s[98:99] op_sel_hi:[1,0]
	v_pk_mul_f32 v[234:235], v[142:143], s[98:99] op_sel:[0,1] op_sel_hi:[1,1]
	v_exp_f32_e32 v234, v234
	v_exp_f32_e32 v235, v235
	s_nop 0
	v_pk_add_f32 v[234:235], v[234:235], s[100:101] op_sel_hi:[1,0]
	v_rcp_f32_e32 v234, v234
	v_rcp_f32_e32 v235, v235
	s_nop 0
	v_pk_mul_f32 v[244:245], v[244:245], v[234:235]
	v_pk_mul_f32 v[244:245], v[244:245], v[138:139]
	global_store_dwordx2 v[8:9], v[6:7], off
	s_nop 0
	s_nop 0
	v_med3_f32 v5, v244, s40, v190
	s_nop 0
	v_pk_mul_f32 v[246:247], v[144:145], s[98:99] op_sel_hi:[1,0]
	v_pk_mul_f32 v[234:235], v[144:145], s[98:99] op_sel:[0,1] op_sel_hi:[1,1]
	v_exp_f32_e32 v234, v234
	v_exp_f32_e32 v235, v235
	s_nop 0
	v_pk_add_f32 v[234:235], v[234:235], s[100:101] op_sel_hi:[1,0]
	v_rcp_f32_e32 v234, v234
	v_rcp_f32_e32 v235, v235
	s_nop 0
	v_pk_mul_f32 v[246:247], v[246:247], v[234:235]
	v_pk_mul_f32 v[246:247], v[246:247], v[140:141]
	v_med3_f32 v7, v245, s40, v190
	s_nop 0
	s_nop 0
	s_nop 0
	v_pk_mul_f32 v[248:249], v[134:135], s[98:99] op_sel_hi:[1,0]
	v_pk_mul_f32 v[234:235], v[134:135], s[98:99] op_sel:[0,1] op_sel_hi:[1,1]
	v_exp_f32_e32 v234, v234
	v_exp_f32_e32 v235, v235
	s_nop 0
	v_pk_add_f32 v[234:235], v[234:235], s[100:101] op_sel_hi:[1,0]
	v_rcp_f32_e32 v234, v234
	v_rcp_f32_e32 v235, v235
	s_nop 0
	v_pk_mul_f32 v[248:249], v[248:249], v[234:235]
	v_pk_mul_f32 v[248:249], v[248:249], v[130:131]
	s_nop 0
	s_nop 0
	s_nop 0
	s_nop 0
	v_pk_mul_f32 v[250:251], v[136:137], s[98:99] op_sel_hi:[1,0]
	v_pk_mul_f32 v[234:235], v[136:137], s[98:99] op_sel:[0,1] op_sel_hi:[1,1]
	v_exp_f32_e32 v234, v234
	v_exp_f32_e32 v235, v235
	s_nop 0
	v_pk_add_f32 v[234:235], v[234:235], s[100:101] op_sel_hi:[1,0]
	v_rcp_f32_e32 v234, v234
	v_rcp_f32_e32 v235, v235
	s_nop 0
	v_pk_mul_f32 v[250:251], v[250:251], v[234:235]
	v_pk_mul_f32 v[250:251], v[250:251], v[132:133]
	s_nop 0
	s_nop 0
	s_nop 0
	s_nop 0
	v_mov_b32_e32 v8, v163
	v_cvt_pk_fp8_f32 v8, v5, v7
	v_med3_f32 v5, v246, s40, v190
	v_med3_f32 v7, v247, s40, v190
	v_mov_b32_e32 v9, v163
	v_cvt_pk_fp8_f32 v8, v5, v7 op_sel:[0,0,1]
	v_med3_f32 v5, v248, s40, v190
	v_med3_f32 v7, v249, s40, v190
	v_cvt_pk_fp8_f32 v9, v5, v7
	v_add_u32_e32 v6, 16, v4
	v_med3_f32 v5, v250, s40, v190
	v_med3_f32 v7, v251, s40, v190
	v_cvt_pk_fp8_f32 v9, v5, v7 op_sel:[0,0,1]
	v_ashrrev_i32_e32 v7, 31, v6
	v_lshlrev_b64 v[6:7], 7, v[6:7]
	v_lshl_add_u64 v[6:7], s[12:13], 0, v[6:7]
	v_lshl_add_u64 v[6:7], v[6:7], 0, v[2:3]
	v_pk_mul_f32 v[236:237], v[126:127], s[98:99] op_sel_hi:[1,0]
	v_pk_mul_f32 v[234:235], v[126:127], s[98:99] op_sel:[0,1] op_sel_hi:[1,1]
	v_exp_f32_e32 v234, v234
	v_exp_f32_e32 v235, v235
	s_nop 0
	v_pk_add_f32 v[234:235], v[234:235], s[100:101] op_sel_hi:[1,0]
	v_rcp_f32_e32 v234, v234
	v_rcp_f32_e32 v235, v235
	s_nop 0
	v_pk_mul_f32 v[236:237], v[236:237], v[234:235]
	v_pk_mul_f32 v[236:237], v[236:237], v[122:123]
	global_store_dwordx2 v[6:7], v[8:9], off
	s_nop 0
	s_nop 0
	v_med3_f32 v5, v236, s40, v190
	s_nop 0
	v_pk_mul_f32 v[238:239], v[128:129], s[98:99] op_sel_hi:[1,0]
	v_pk_mul_f32 v[234:235], v[128:129], s[98:99] op_sel:[0,1] op_sel_hi:[1,1]
	v_exp_f32_e32 v234, v234
	v_exp_f32_e32 v235, v235
	s_nop 0
	v_pk_add_f32 v[234:235], v[234:235], s[100:101] op_sel_hi:[1,0]
	v_rcp_f32_e32 v234, v234
	v_rcp_f32_e32 v235, v235
	s_nop 0
	v_pk_mul_f32 v[238:239], v[238:239], v[234:235]
	v_pk_mul_f32 v[238:239], v[238:239], v[124:125]
	v_med3_f32 v7, v237, s40, v190
	s_nop 0
	s_nop 0
	s_nop 0
	v_pk_mul_f32 v[240:241], v[118:119], s[98:99] op_sel_hi:[1,0]
	v_pk_mul_f32 v[234:235], v[118:119], s[98:99] op_sel:[0,1] op_sel_hi:[1,1]
	v_exp_f32_e32 v234, v234
	v_exp_f32_e32 v235, v235
	s_nop 0
	v_pk_add_f32 v[234:235], v[234:235], s[100:101] op_sel_hi:[1,0]
	v_rcp_f32_e32 v234, v234
	v_rcp_f32_e32 v235, v235
	s_nop 0
	v_pk_mul_f32 v[240:241], v[240:241], v[234:235]
	v_pk_mul_f32 v[240:241], v[240:241], v[114:115]
	s_nop 0
	s_nop 0
	s_nop 0
	s_nop 0
	v_pk_mul_f32 v[242:243], v[120:121], s[98:99] op_sel_hi:[1,0]
	v_pk_mul_f32 v[234:235], v[120:121], s[98:99] op_sel:[0,1] op_sel_hi:[1,1]
	v_exp_f32_e32 v234, v234
	v_exp_f32_e32 v235, v235
	s_nop 0
	v_pk_add_f32 v[234:235], v[234:235], s[100:101] op_sel_hi:[1,0]
	v_rcp_f32_e32 v234, v234
	v_rcp_f32_e32 v235, v235
	s_nop 0
	v_pk_mul_f32 v[242:243], v[242:243], v[234:235]
	v_pk_mul_f32 v[242:243], v[242:243], v[116:117]
	s_nop 0
	s_nop 0
	s_nop 0
	s_nop 0
	v_mov_b32_e32 v8, v163
	v_cvt_pk_fp8_f32 v8, v5, v7
	v_med3_f32 v5, v238, s40, v190
	v_med3_f32 v7, v239, s40, v190
	v_mov_b32_e32 v9, v163
	v_cvt_pk_fp8_f32 v8, v5, v7 op_sel:[0,0,1]
	v_med3_f32 v5, v240, s40, v190
	v_med3_f32 v7, v241, s40, v190
	v_cvt_pk_fp8_f32 v9, v5, v7
	v_add_u32_e32 v6, 32, v4
	v_med3_f32 v5, v242, s40, v190
	v_med3_f32 v7, v243, s40, v190
	v_cvt_pk_fp8_f32 v9, v5, v7 op_sel:[0,0,1]
	v_ashrrev_i32_e32 v7, 31, v6
	v_lshlrev_b64 v[6:7], 7, v[6:7]
	v_lshl_add_u64 v[6:7], s[12:13], 0, v[6:7]
	v_lshl_add_u64 v[6:7], v[6:7], 0, v[2:3]
	v_pk_mul_f32 v[244:245], v[110:111], s[98:99] op_sel_hi:[1,0]
	v_pk_mul_f32 v[234:235], v[110:111], s[98:99] op_sel:[0,1] op_sel_hi:[1,1]
	v_exp_f32_e32 v234, v234
	v_exp_f32_e32 v235, v235
	s_nop 0
	v_pk_add_f32 v[234:235], v[234:235], s[100:101] op_sel_hi:[1,0]
	v_rcp_f32_e32 v234, v234
	v_rcp_f32_e32 v235, v235
	s_nop 0
	v_pk_mul_f32 v[244:245], v[244:245], v[234:235]
	v_pk_mul_f32 v[244:245], v[244:245], v[106:107]
	global_store_dwordx2 v[6:7], v[8:9], off
	s_nop 0
	s_nop 0
	v_med3_f32 v5, v244, s40, v190
	s_nop 0
	v_pk_mul_f32 v[246:247], v[112:113], s[98:99] op_sel_hi:[1,0]
	v_pk_mul_f32 v[234:235], v[112:113], s[98:99] op_sel:[0,1] op_sel_hi:[1,1]
	v_exp_f32_e32 v234, v234
	v_exp_f32_e32 v235, v235
	s_nop 0
	v_pk_add_f32 v[234:235], v[234:235], s[100:101] op_sel_hi:[1,0]
	v_rcp_f32_e32 v234, v234
	v_rcp_f32_e32 v235, v235
	s_nop 0
	v_pk_mul_f32 v[246:247], v[246:247], v[234:235]
	v_pk_mul_f32 v[246:247], v[246:247], v[108:109]
	v_med3_f32 v7, v245, s40, v190
	s_nop 0
	s_nop 0
	s_nop 0
	v_pk_mul_f32 v[248:249], v[102:103], s[98:99] op_sel_hi:[1,0]
	v_pk_mul_f32 v[234:235], v[102:103], s[98:99] op_sel:[0,1] op_sel_hi:[1,1]
	v_exp_f32_e32 v234, v234
	v_exp_f32_e32 v235, v235
	s_nop 0
	v_pk_add_f32 v[234:235], v[234:235], s[100:101] op_sel_hi:[1,0]
	v_rcp_f32_e32 v234, v234
	v_rcp_f32_e32 v235, v235
	s_nop 0
	v_pk_mul_f32 v[248:249], v[248:249], v[234:235]
	v_pk_mul_f32 v[248:249], v[248:249], v[98:99]
	s_nop 0
	s_nop 0
	s_nop 0
	s_nop 0
	v_pk_mul_f32 v[250:251], v[104:105], s[98:99] op_sel_hi:[1,0]
	v_pk_mul_f32 v[234:235], v[104:105], s[98:99] op_sel:[0,1] op_sel_hi:[1,1]
	v_exp_f32_e32 v234, v234
	v_exp_f32_e32 v235, v235
	s_nop 0
	v_pk_add_f32 v[234:235], v[234:235], s[100:101] op_sel_hi:[1,0]
	v_rcp_f32_e32 v234, v234
	v_rcp_f32_e32 v235, v235
	s_nop 0
	v_pk_mul_f32 v[250:251], v[250:251], v[234:235]
	v_pk_mul_f32 v[250:251], v[250:251], v[100:101]
	s_nop 0
	s_nop 0
	s_nop 0
	s_nop 0
	v_mov_b32_e32 v8, v163
	v_cvt_pk_fp8_f32 v8, v5, v7
	v_med3_f32 v5, v246, s40, v190
	v_med3_f32 v7, v247, s40, v190
	v_mov_b32_e32 v9, v163
	v_cvt_pk_fp8_f32 v8, v5, v7 op_sel:[0,0,1]
	v_med3_f32 v5, v248, s40, v190
	v_med3_f32 v7, v249, s40, v190
	v_cvt_pk_fp8_f32 v9, v5, v7
	v_add_u32_e32 v6, 48, v4
	v_med3_f32 v5, v250, s40, v190
	v_med3_f32 v7, v251, s40, v190
	v_cvt_pk_fp8_f32 v9, v5, v7 op_sel:[0,0,1]
	v_ashrrev_i32_e32 v7, 31, v6
	v_lshlrev_b64 v[6:7], 7, v[6:7]
	v_lshl_add_u64 v[6:7], s[12:13], 0, v[6:7]
	v_lshl_add_u64 v[6:7], v[6:7], 0, v[2:3]
	v_pk_mul_f32 v[236:237], v[94:95], s[98:99] op_sel_hi:[1,0]
	v_pk_mul_f32 v[234:235], v[94:95], s[98:99] op_sel:[0,1] op_sel_hi:[1,1]
	v_exp_f32_e32 v234, v234
	v_exp_f32_e32 v235, v235
	s_nop 0
	v_pk_add_f32 v[234:235], v[234:235], s[100:101] op_sel_hi:[1,0]
	v_rcp_f32_e32 v234, v234
	v_rcp_f32_e32 v235, v235
	s_nop 0
	v_pk_mul_f32 v[236:237], v[236:237], v[234:235]
	v_pk_mul_f32 v[236:237], v[236:237], v[90:91]
	global_store_dwordx2 v[6:7], v[8:9], off
	v_add_u32_e32 v6, 0x80, v4
	s_nop 0
	v_med3_f32 v5, v236, s40, v190
	s_nop 0
	v_pk_mul_f32 v[238:239], v[96:97], s[98:99] op_sel_hi:[1,0]
	v_pk_mul_f32 v[234:235], v[96:97], s[98:99] op_sel:[0,1] op_sel_hi:[1,1]
	v_exp_f32_e32 v234, v234
	v_exp_f32_e32 v235, v235
	s_nop 0
	v_pk_add_f32 v[234:235], v[234:235], s[100:101] op_sel_hi:[1,0]
	v_rcp_f32_e32 v234, v234
	v_rcp_f32_e32 v235, v235
	s_nop 0
	v_pk_mul_f32 v[238:239], v[238:239], v[234:235]
	v_pk_mul_f32 v[238:239], v[238:239], v[92:93]
	v_med3_f32 v7, v237, s40, v190
	s_nop 0
	s_nop 0
	s_nop 0
	v_pk_mul_f32 v[240:241], v[86:87], s[98:99] op_sel_hi:[1,0]
	v_pk_mul_f32 v[234:235], v[86:87], s[98:99] op_sel:[0,1] op_sel_hi:[1,1]
	v_exp_f32_e32 v234, v234
	v_exp_f32_e32 v235, v235
	s_nop 0
	v_pk_add_f32 v[234:235], v[234:235], s[100:101] op_sel_hi:[1,0]
	v_rcp_f32_e32 v234, v234
	v_rcp_f32_e32 v235, v235
	s_nop 0
	v_pk_mul_f32 v[240:241], v[240:241], v[234:235]
	v_pk_mul_f32 v[240:241], v[240:241], v[82:83]
	s_nop 0
	s_nop 0
	s_nop 0
	s_nop 0
	v_pk_mul_f32 v[242:243], v[88:89], s[98:99] op_sel_hi:[1,0]
	v_pk_mul_f32 v[234:235], v[88:89], s[98:99] op_sel:[0,1] op_sel_hi:[1,1]
	v_exp_f32_e32 v234, v234
	v_exp_f32_e32 v235, v235
	s_nop 0
	v_pk_add_f32 v[234:235], v[234:235], s[100:101] op_sel_hi:[1,0]
	v_rcp_f32_e32 v234, v234
	v_rcp_f32_e32 v235, v235
	s_nop 0
	v_pk_mul_f32 v[242:243], v[242:243], v[234:235]
	v_pk_mul_f32 v[242:243], v[242:243], v[84:85]
	s_nop 0
	s_nop 0
	s_nop 0
	s_nop 0
	v_mov_b32_e32 v8, v163
	v_cvt_pk_fp8_f32 v8, v5, v7
	v_med3_f32 v5, v238, s40, v190
	v_med3_f32 v7, v239, s40, v190
	v_mov_b32_e32 v9, v163
	v_cvt_pk_fp8_f32 v8, v5, v7 op_sel:[0,0,1]
	v_med3_f32 v5, v240, s40, v190
	v_med3_f32 v7, v241, s40, v190
	v_cvt_pk_fp8_f32 v9, v5, v7
	v_med3_f32 v5, v242, s40, v190
	v_med3_f32 v7, v243, s40, v190
	v_cvt_pk_fp8_f32 v9, v5, v7 op_sel:[0,0,1]
	v_ashrrev_i32_e32 v7, 31, v6
	v_lshlrev_b64 v[6:7], 7, v[6:7]
	v_lshl_add_u64 v[6:7], s[12:13], 0, v[6:7]
	v_lshl_add_u64 v[6:7], v[6:7], 0, v[2:3]
	v_pk_mul_f32 v[244:245], v[78:79], s[98:99] op_sel_hi:[1,0]
	v_pk_mul_f32 v[234:235], v[78:79], s[98:99] op_sel:[0,1] op_sel_hi:[1,1]
	v_exp_f32_e32 v234, v234
	v_exp_f32_e32 v235, v235
	s_nop 0
	v_pk_add_f32 v[234:235], v[234:235], s[100:101] op_sel_hi:[1,0]
	v_rcp_f32_e32 v234, v234
	v_rcp_f32_e32 v235, v235
	s_nop 0
	v_pk_mul_f32 v[244:245], v[244:245], v[234:235]
	v_pk_mul_f32 v[244:245], v[244:245], v[74:75]
	global_store_dwordx2 v[6:7], v[8:9], off
	s_nop 0
	s_nop 0
	v_med3_f32 v5, v244, s40, v190
	s_nop 0
	v_pk_mul_f32 v[246:247], v[80:81], s[98:99] op_sel_hi:[1,0]
	v_pk_mul_f32 v[234:235], v[80:81], s[98:99] op_sel:[0,1] op_sel_hi:[1,1]
	v_exp_f32_e32 v234, v234
	v_exp_f32_e32 v235, v235
	s_nop 0
	v_pk_add_f32 v[234:235], v[234:235], s[100:101] op_sel_hi:[1,0]
	v_rcp_f32_e32 v234, v234
	v_rcp_f32_e32 v235, v235
	s_nop 0
	v_pk_mul_f32 v[246:247], v[246:247], v[234:235]
	v_pk_mul_f32 v[246:247], v[246:247], v[76:77]
	v_med3_f32 v7, v245, s40, v190
	s_nop 0
	s_nop 0
	s_nop 0
	v_pk_mul_f32 v[248:249], v[70:71], s[98:99] op_sel_hi:[1,0]
	v_pk_mul_f32 v[234:235], v[70:71], s[98:99] op_sel:[0,1] op_sel_hi:[1,1]
	v_exp_f32_e32 v234, v234
	v_exp_f32_e32 v235, v235
	s_nop 0
	v_pk_add_f32 v[234:235], v[234:235], s[100:101] op_sel_hi:[1,0]
	v_rcp_f32_e32 v234, v234
	v_rcp_f32_e32 v235, v235
	s_nop 0
	v_pk_mul_f32 v[248:249], v[248:249], v[234:235]
	v_pk_mul_f32 v[248:249], v[248:249], v[66:67]
	s_nop 0
	s_nop 0
	s_nop 0
	s_nop 0
	v_pk_mul_f32 v[250:251], v[72:73], s[98:99] op_sel_hi:[1,0]
	v_pk_mul_f32 v[234:235], v[72:73], s[98:99] op_sel:[0,1] op_sel_hi:[1,1]
	v_exp_f32_e32 v234, v234
	v_exp_f32_e32 v235, v235
	s_nop 0
	v_pk_add_f32 v[234:235], v[234:235], s[100:101] op_sel_hi:[1,0]
	v_rcp_f32_e32 v234, v234
	v_rcp_f32_e32 v235, v235
	s_nop 0
	v_pk_mul_f32 v[250:251], v[250:251], v[234:235]
	v_pk_mul_f32 v[250:251], v[250:251], v[68:69]
	s_nop 0
	s_nop 0
	s_nop 0
	s_nop 0
	v_mov_b32_e32 v8, v163
	v_cvt_pk_fp8_f32 v8, v5, v7
	v_med3_f32 v5, v246, s40, v190
	v_med3_f32 v7, v247, s40, v190
	v_mov_b32_e32 v9, v163
	v_cvt_pk_fp8_f32 v8, v5, v7 op_sel:[0,0,1]
	v_med3_f32 v5, v248, s40, v190
	v_med3_f32 v7, v249, s40, v190
	v_cvt_pk_fp8_f32 v9, v5, v7
	v_add_u32_e32 v6, 0x90, v4
	v_med3_f32 v5, v250, s40, v190
	v_med3_f32 v7, v251, s40, v190
	v_cvt_pk_fp8_f32 v9, v5, v7 op_sel:[0,0,1]
	v_ashrrev_i32_e32 v7, 31, v6
	v_lshlrev_b64 v[6:7], 7, v[6:7]
	v_lshl_add_u64 v[6:7], s[12:13], 0, v[6:7]
	v_lshl_add_u64 v[6:7], v[6:7], 0, v[2:3]
	v_pk_mul_f32 v[236:237], v[62:63], s[98:99] op_sel_hi:[1,0]
	v_pk_mul_f32 v[234:235], v[62:63], s[98:99] op_sel:[0,1] op_sel_hi:[1,1]
	v_exp_f32_e32 v234, v234
	v_exp_f32_e32 v235, v235
	s_nop 0
	v_pk_add_f32 v[234:235], v[234:235], s[100:101] op_sel_hi:[1,0]
	v_rcp_f32_e32 v234, v234
	v_rcp_f32_e32 v235, v235
	s_nop 0
	v_pk_mul_f32 v[236:237], v[236:237], v[234:235]
	v_pk_mul_f32 v[236:237], v[236:237], v[58:59]
	global_store_dwordx2 v[6:7], v[8:9], off
	s_nop 0
	s_nop 0
	v_med3_f32 v5, v236, s40, v190
	s_nop 0
	v_pk_mul_f32 v[238:239], v[64:65], s[98:99] op_sel_hi:[1,0]
	v_pk_mul_f32 v[234:235], v[64:65], s[98:99] op_sel:[0,1] op_sel_hi:[1,1]
	v_exp_f32_e32 v234, v234
	v_exp_f32_e32 v235, v235
	s_nop 0
	v_pk_add_f32 v[234:235], v[234:235], s[100:101] op_sel_hi:[1,0]
	v_rcp_f32_e32 v234, v234
	v_rcp_f32_e32 v235, v235
	s_nop 0
	v_pk_mul_f32 v[238:239], v[238:239], v[234:235]
	v_pk_mul_f32 v[238:239], v[238:239], v[60:61]
	v_med3_f32 v7, v237, s40, v190
	s_nop 0
	s_nop 0
	s_nop 0
	v_pk_mul_f32 v[240:241], v[54:55], s[98:99] op_sel_hi:[1,0]
	v_pk_mul_f32 v[234:235], v[54:55], s[98:99] op_sel:[0,1] op_sel_hi:[1,1]
	v_exp_f32_e32 v234, v234
	v_exp_f32_e32 v235, v235
	s_nop 0
	v_pk_add_f32 v[234:235], v[234:235], s[100:101] op_sel_hi:[1,0]
	v_rcp_f32_e32 v234, v234
	v_rcp_f32_e32 v235, v235
	s_nop 0
	v_pk_mul_f32 v[240:241], v[240:241], v[234:235]
	v_pk_mul_f32 v[240:241], v[240:241], v[50:51]
	s_nop 0
	s_nop 0
	s_nop 0
	s_nop 0
	v_pk_mul_f32 v[242:243], v[56:57], s[98:99] op_sel_hi:[1,0]
	v_pk_mul_f32 v[234:235], v[56:57], s[98:99] op_sel:[0,1] op_sel_hi:[1,1]
	v_exp_f32_e32 v234, v234
	v_exp_f32_e32 v235, v235
	s_nop 0
	v_pk_add_f32 v[234:235], v[234:235], s[100:101] op_sel_hi:[1,0]
	v_rcp_f32_e32 v234, v234
	v_rcp_f32_e32 v235, v235
	s_nop 0
	v_pk_mul_f32 v[242:243], v[242:243], v[234:235]
	v_pk_mul_f32 v[242:243], v[242:243], v[52:53]
	s_nop 0
	s_nop 0
	s_nop 0
	s_nop 0
	v_mov_b32_e32 v8, v163
	v_cvt_pk_fp8_f32 v8, v5, v7
	v_med3_f32 v5, v238, s40, v190
	v_med3_f32 v7, v239, s40, v190
	v_mov_b32_e32 v9, v163
	v_cvt_pk_fp8_f32 v8, v5, v7 op_sel:[0,0,1]
	v_med3_f32 v5, v240, s40, v190
	v_med3_f32 v7, v241, s40, v190
	v_cvt_pk_fp8_f32 v9, v5, v7
	v_add_u32_e32 v6, 0xa0, v4
	v_med3_f32 v5, v242, s40, v190
	v_med3_f32 v7, v243, s40, v190
	v_cvt_pk_fp8_f32 v9, v5, v7 op_sel:[0,0,1]
	v_ashrrev_i32_e32 v7, 31, v6
	v_lshlrev_b64 v[6:7], 7, v[6:7]
	v_lshl_add_u64 v[6:7], s[12:13], 0, v[6:7]
	v_lshl_add_u64 v[6:7], v[6:7], 0, v[2:3]
	v_pk_mul_f32 v[244:245], v[46:47], s[98:99] op_sel_hi:[1,0]
	v_pk_mul_f32 v[234:235], v[46:47], s[98:99] op_sel:[0,1] op_sel_hi:[1,1]
	v_exp_f32_e32 v234, v234
	v_exp_f32_e32 v235, v235
	s_nop 0
	v_pk_add_f32 v[234:235], v[234:235], s[100:101] op_sel_hi:[1,0]
	v_rcp_f32_e32 v234, v234
	v_rcp_f32_e32 v235, v235
	s_nop 0
	v_pk_mul_f32 v[244:245], v[244:245], v[234:235]
	v_pk_mul_f32 v[244:245], v[244:245], v[42:43]
	global_store_dwordx2 v[6:7], v[8:9], off
	v_add_u32_e32 v4, 0xb0, v4
	s_nop 0
	v_med3_f32 v5, v244, s40, v190
	s_nop 0
	v_pk_mul_f32 v[246:247], v[48:49], s[98:99] op_sel_hi:[1,0]
	v_pk_mul_f32 v[234:235], v[48:49], s[98:99] op_sel:[0,1] op_sel_hi:[1,1]
	v_exp_f32_e32 v234, v234
	v_exp_f32_e32 v235, v235
	s_nop 0
	v_pk_add_f32 v[234:235], v[234:235], s[100:101] op_sel_hi:[1,0]
	v_rcp_f32_e32 v234, v234
	v_rcp_f32_e32 v235, v235
	s_nop 0
	v_pk_mul_f32 v[246:247], v[246:247], v[234:235]
	v_pk_mul_f32 v[246:247], v[246:247], v[44:45]
	s_nop 0
	s_nop 0
	v_pk_mul_f32 v[248:249], v[38:39], s[98:99] op_sel_hi:[1,0]
	v_pk_mul_f32 v[234:235], v[38:39], s[98:99] op_sel:[0,1] op_sel_hi:[1,1]
	v_exp_f32_e32 v234, v234
	v_exp_f32_e32 v235, v235
	s_nop 0
	v_pk_add_f32 v[234:235], v[234:235], s[100:101] op_sel_hi:[1,0]
	v_rcp_f32_e32 v234, v234
	v_rcp_f32_e32 v235, v235
	s_nop 0
	v_pk_mul_f32 v[248:249], v[248:249], v[234:235]
	v_pk_mul_f32 v[248:249], v[248:249], v[34:35]
	s_nop 0
	s_nop 0
	v_pk_mul_f32 v[250:251], v[40:41], s[98:99] op_sel_hi:[1,0]
	v_pk_mul_f32 v[234:235], v[40:41], s[98:99] op_sel:[0,1] op_sel_hi:[1,1]
	v_exp_f32_e32 v234, v234
	v_exp_f32_e32 v235, v235
	s_nop 0
	v_pk_add_f32 v[234:235], v[234:235], s[100:101] op_sel_hi:[1,0]
	v_rcp_f32_e32 v234, v234
	v_rcp_f32_e32 v235, v235
	s_nop 0
	v_pk_mul_f32 v[250:251], v[250:251], v[234:235]
	v_pk_mul_f32 v[250:251], v[250:251], v[36:37]
	s_nop 0
	s_nop 0
	v_med3_f32 v13, v245, s40, v190
	v_mov_b32_e32 v6, v163
	v_cvt_pk_fp8_f32 v6, v5, v13
	v_med3_f32 v5, v246, s40, v190
	v_med3_f32 v7, v247, s40, v190
	v_med3_f32 v8, v249, s40, v190
	v_cvt_pk_fp8_f32 v6, v5, v7 op_sel:[0,0,1]
	v_med3_f32 v5, v248, s40, v190
	v_mov_b32_e32 v7, v163
	v_cvt_pk_fp8_f32 v7, v5, v8
	v_med3_f32 v5, v250, s40, v190
	v_med3_f32 v8, v251, s40, v190
	v_cvt_pk_fp8_f32 v7, v5, v8 op_sel:[0,0,1]
	v_ashrrev_i32_e32 v5, 31, v4
	v_lshlrev_b64 v[4:5], 7, v[4:5]
	v_lshl_add_u64 v[4:5], s[12:13], 0, v[4:5]
	v_lshl_add_u64 v[2:3], v[4:5], 0, v[2:3]
	global_store_dwordx2 v[2:3], v[6:7], off
	s_cbranch_vccz .LBB0_1291
	s_waitcnt vmcnt(0)
	s_cmpk_gt_u32 s42, 0xff
	s_cbranch_scc1 .LBB0_1237
	s_barrier
	s_branch .LBB0_1237

.Lpeel_exit_11:
	s_mov_b32 s98, 0x3b000000
	s_mov_b32 s99, 0xbcb8aa3b
	s_mov_b32 s100, 1.0
	v_pk_mul_f32 v[236:237], v[158:159], s[98:99] op_sel_hi:[1,0]
	v_pk_mul_f32 v[234:235], v[158:159], s[98:99] op_sel:[0,1] op_sel_hi:[1,1]
	v_exp_f32_e32 v234, v234
	v_exp_f32_e32 v235, v235
	s_nop 0
	v_pk_add_f32 v[234:235], v[234:235], s[100:101] op_sel_hi:[1,0]
	v_rcp_f32_e32 v234, v234
	v_rcp_f32_e32 v235, v235
	s_nop 0
	v_pk_mul_f32 v[236:237], v[236:237], v[234:235]
	v_pk_mul_f32 v[236:237], v[236:237], v[154:155]
	s_ashr_i32 s35, s34, 31
	s_ashr_i32 s31, s30, 31
	s_lshl_b64 s[14:15], s[34:35], 18
	s_lshl_b64 s[30:31], s[30:31], 15
	v_mov_b32_e32 v3, v195
	s_add_u32 s0, s6, s14
	v_med3_f32 v5, v236, s10, v190
	s_nop 15
	s_nop 15
	v_mov_b32_e32 v2, v196
	v_pk_mul_f32 v[238:239], v[160:161], s[98:99] op_sel_hi:[1,0]
	v_pk_mul_f32 v[234:235], v[160:161], s[98:99] op_sel:[0,1] op_sel_hi:[1,1]
	v_exp_f32_e32 v234, v234
	v_exp_f32_e32 v235, v235
	s_nop 0
	v_pk_add_f32 v[234:235], v[234:235], s[100:101] op_sel_hi:[1,0]
	v_rcp_f32_e32 v234, v234
	v_rcp_f32_e32 v235, v235
	s_nop 0
	v_pk_mul_f32 v[238:239], v[238:239], v[234:235]
	v_pk_mul_f32 v[238:239], v[238:239], v[156:157]
	v_add_u32_e32 v4, s49, v3
	s_addc_u32 s1, s7, s15
	s_add_u32 s14, s0, s30
	v_lshl_add_u32 v2, v2, 3, s50
	s_addc_u32 s15, s1, s31
	v_ashrrev_i32_e32 v3, 31, v2
	s_and_b64 vcc, exec, s[12:13]
	v_pk_mul_f32 v[240:241], v[150:151], s[98:99] op_sel_hi:[1,0]
	v_pk_mul_f32 v[234:235], v[150:151], s[98:99] op_sel:[0,1] op_sel_hi:[1,1]
	v_exp_f32_e32 v234, v234
	v_exp_f32_e32 v235, v235
	s_nop 0
	v_pk_add_f32 v[234:235], v[234:235], s[100:101] op_sel_hi:[1,0]
	v_rcp_f32_e32 v234, v234
	v_rcp_f32_e32 v235, v235
	s_nop 0
	v_pk_mul_f32 v[240:241], v[240:241], v[234:235]
	v_pk_mul_f32 v[240:241], v[240:241], v[146:147]
	v_mov_b32_e32 v174, v200
	v_mov_b32_e32 v172, v199
	v_mov_b32_e32 v170, v198
	v_mov_b32_e32 v168, v171
	s_mov_b32 s30, s28
	s_mov_b32 s34, s54
	s_mov_b64 s[36:37], s[16:17]
	v_pk_mul_f32 v[242:243], v[152:153], s[98:99] op_sel_hi:[1,0]
	v_pk_mul_f32 v[234:235], v[152:153], s[98:99] op_sel:[0,1] op_sel_hi:[1,1]
	v_exp_f32_e32 v234, v234
	v_exp_f32_e32 v235, v235
	s_nop 0
	v_pk_add_f32 v[234:235], v[234:235], s[100:101] op_sel_hi:[1,0]
	v_rcp_f32_e32 v234, v234
	v_rcp_f32_e32 v235, v235
	s_nop 0
	v_pk_mul_f32 v[242:243], v[242:243], v[234:235]
	v_pk_mul_f32 v[242:243], v[242:243], v[148:149]
	s_nop 0
	s_nop 0
	v_med3_f32 v13, v237, s10, v190
	v_mov_b32_e32 v6, v163
	v_cvt_pk_fp8_f32 v6, v5, v13
	v_med3_f32 v5, v238, s10, v190
	v_med3_f32 v7, v239, s10, v190
	v_med3_f32 v8, v241, s10, v190
	v_cvt_pk_fp8_f32 v6, v5, v7 op_sel:[0,0,1]
	v_med3_f32 v5, v240, s10, v190
	v_mov_b32_e32 v7, v163
	v_cvt_pk_fp8_f32 v7, v5, v8
	v_med3_f32 v5, v242, s10, v190
	v_med3_f32 v8, v243, s10, v190
	v_cvt_pk_fp8_f32 v7, v5, v8 op_sel:[0,0,1]
	v_ashrrev_i32_e32 v5, 31, v4
	v_lshlrev_b64 v[8:9], 7, v[4:5]
	v_lshl_add_u64 v[8:9], s[14:15], 0, v[8:9]
	v_lshl_add_u64 v[8:9], v[8:9], 0, v[2:3]
	v_pk_mul_f32 v[244:245], v[142:143], s[98:99] op_sel_hi:[1,0]
	v_pk_mul_f32 v[234:235], v[142:143], s[98:99] op_sel:[0,1] op_sel_hi:[1,1]
	v_exp_f32_e32 v234, v234
	v_exp_f32_e32 v235, v235
	s_nop 0
	v_pk_add_f32 v[234:235], v[234:235], s[100:101] op_sel_hi:[1,0]
	v_rcp_f32_e32 v234, v234
	v_rcp_f32_e32 v235, v235
	s_nop 0
	v_pk_mul_f32 v[244:245], v[244:245], v[234:235]
	v_pk_mul_f32 v[244:245], v[244:245], v[138:139]
	global_store_dwordx2 v[8:9], v[6:7], off
	s_nop 0
	s_nop 0
	v_med3_f32 v5, v244, s10, v190
	s_nop 0
	v_pk_mul_f32 v[246:247], v[144:145], s[98:99] op_sel_hi:[1,0]
	v_pk_mul_f32 v[234:235], v[144:145], s[98:99] op_sel:[0,1] op_sel_hi:[1,1]
	v_exp_f32_e32 v234, v234
	v_exp_f32_e32 v235, v235
	s_nop 0
	v_pk_add_f32 v[234:235], v[234:235], s[100:101] op_sel_hi:[1,0]
	v_rcp_f32_e32 v234, v234
	v_rcp_f32_e32 v235, v235
	s_nop 0
	v_pk_mul_f32 v[246:247], v[246:247], v[234:235]
	v_pk_mul_f32 v[246:247], v[246:247], v[140:141]
	v_med3_f32 v7, v245, s10, v190
	s_nop 0
	s_nop 0
	s_nop 0
	v_pk_mul_f32 v[248:249], v[134:135], s[98:99] op_sel_hi:[1,0]
	v_pk_mul_f32 v[234:235], v[134:135], s[98:99] op_sel:[0,1] op_sel_hi:[1,1]
	v_exp_f32_e32 v234, v234
	v_exp_f32_e32 v235, v235
	s_nop 0
	v_pk_add_f32 v[234:235], v[234:235], s[100:101] op_sel_hi:[1,0]
	v_rcp_f32_e32 v234, v234
	v_rcp_f32_e32 v235, v235
	s_nop 0
	v_pk_mul_f32 v[248:249], v[248:249], v[234:235]
	v_pk_mul_f32 v[248:249], v[248:249], v[130:131]
	s_nop 0
	s_nop 0
	s_nop 0
	s_nop 0
	v_pk_mul_f32 v[250:251], v[136:137], s[98:99] op_sel_hi:[1,0]
	v_pk_mul_f32 v[234:235], v[136:137], s[98:99] op_sel:[0,1] op_sel_hi:[1,1]
	v_exp_f32_e32 v234, v234
	v_exp_f32_e32 v235, v235
	s_nop 0
	v_pk_add_f32 v[234:235], v[234:235], s[100:101] op_sel_hi:[1,0]
	v_rcp_f32_e32 v234, v234
	v_rcp_f32_e32 v235, v235
	s_nop 0
	v_pk_mul_f32 v[250:251], v[250:251], v[234:235]
	v_pk_mul_f32 v[250:251], v[250:251], v[132:133]
	s_nop 0
	s_nop 0
	s_nop 0
	s_nop 0
	v_mov_b32_e32 v8, v163
	v_cvt_pk_fp8_f32 v8, v5, v7
	v_med3_f32 v5, v246, s10, v190
	v_med3_f32 v7, v247, s10, v190
	v_mov_b32_e32 v9, v163
	v_cvt_pk_fp8_f32 v8, v5, v7 op_sel:[0,0,1]
	v_med3_f32 v5, v248, s10, v190
	v_med3_f32 v7, v249, s10, v190
	v_cvt_pk_fp8_f32 v9, v5, v7
	v_add_u32_e32 v6, 16, v4
	v_med3_f32 v5, v250, s10, v190
	v_med3_f32 v7, v251, s10, v190
	v_cvt_pk_fp8_f32 v9, v5, v7 op_sel:[0,0,1]
	v_ashrrev_i32_e32 v7, 31, v6
	v_lshlrev_b64 v[6:7], 7, v[6:7]
	v_lshl_add_u64 v[6:7], s[14:15], 0, v[6:7]
	v_lshl_add_u64 v[6:7], v[6:7], 0, v[2:3]
	v_pk_mul_f32 v[236:237], v[126:127], s[98:99] op_sel_hi:[1,0]
	v_pk_mul_f32 v[234:235], v[126:127], s[98:99] op_sel:[0,1] op_sel_hi:[1,1]
	v_exp_f32_e32 v234, v234
	v_exp_f32_e32 v235, v235
	s_nop 0
	v_pk_add_f32 v[234:235], v[234:235], s[100:101] op_sel_hi:[1,0]
	v_rcp_f32_e32 v234, v234
	v_rcp_f32_e32 v235, v235
	s_nop 0
	v_pk_mul_f32 v[236:237], v[236:237], v[234:235]
	v_pk_mul_f32 v[236:237], v[236:237], v[122:123]
	global_store_dwordx2 v[6:7], v[8:9], off
	s_nop 0
	s_nop 0
	v_med3_f32 v5, v236, s10, v190
	s_nop 0
	v_pk_mul_f32 v[238:239], v[128:129], s[98:99] op_sel_hi:[1,0]
	v_pk_mul_f32 v[234:235], v[128:129], s[98:99] op_sel:[0,1] op_sel_hi:[1,1]
	v_exp_f32_e32 v234, v234
	v_exp_f32_e32 v235, v235
	s_nop 0
	v_pk_add_f32 v[234:235], v[234:235], s[100:101] op_sel_hi:[1,0]
	v_rcp_f32_e32 v234, v234
	v_rcp_f32_e32 v235, v235
	s_nop 0
	v_pk_mul_f32 v[238:239], v[238:239], v[234:235]
	v_pk_mul_f32 v[238:239], v[238:239], v[124:125]
	v_med3_f32 v7, v237, s10, v190
	s_nop 0
	s_nop 0
	s_nop 0
	v_pk_mul_f32 v[240:241], v[118:119], s[98:99] op_sel_hi:[1,0]
	v_pk_mul_f32 v[234:235], v[118:119], s[98:99] op_sel:[0,1] op_sel_hi:[1,1]
	v_exp_f32_e32 v234, v234
	v_exp_f32_e32 v235, v235
	s_nop 0
	v_pk_add_f32 v[234:235], v[234:235], s[100:101] op_sel_hi:[1,0]
	v_rcp_f32_e32 v234, v234
	v_rcp_f32_e32 v235, v235
	s_nop 0
	v_pk_mul_f32 v[240:241], v[240:241], v[234:235]
	v_pk_mul_f32 v[240:241], v[240:241], v[114:115]
	s_nop 0
	s_nop 0
	s_nop 0
	s_nop 0
	v_pk_mul_f32 v[242:243], v[120:121], s[98:99] op_sel_hi:[1,0]
	v_pk_mul_f32 v[234:235], v[120:121], s[98:99] op_sel:[0,1] op_sel_hi:[1,1]
	v_exp_f32_e32 v234, v234
	v_exp_f32_e32 v235, v235
	s_nop 0
	v_pk_add_f32 v[234:235], v[234:235], s[100:101] op_sel_hi:[1,0]
	v_rcp_f32_e32 v234, v234
	v_rcp_f32_e32 v235, v235
	s_nop 0
	v_pk_mul_f32 v[242:243], v[242:243], v[234:235]
	v_pk_mul_f32 v[242:243], v[242:243], v[116:117]
	s_nop 0
	s_nop 0
	s_nop 0
	s_nop 0
	v_mov_b32_e32 v8, v163
	v_cvt_pk_fp8_f32 v8, v5, v7
	v_med3_f32 v5, v238, s10, v190
	v_med3_f32 v7, v239, s10, v190
	v_mov_b32_e32 v9, v163
	v_cvt_pk_fp8_f32 v8, v5, v7 op_sel:[0,0,1]
	v_med3_f32 v5, v240, s10, v190
	v_med3_f32 v7, v241, s10, v190
	v_cvt_pk_fp8_f32 v9, v5, v7
	v_add_u32_e32 v6, 32, v4
	v_med3_f32 v5, v242, s10, v190
	v_med3_f32 v7, v243, s10, v190
	v_cvt_pk_fp8_f32 v9, v5, v7 op_sel:[0,0,1]
	v_ashrrev_i32_e32 v7, 31, v6
	v_lshlrev_b64 v[6:7], 7, v[6:7]
	v_lshl_add_u64 v[6:7], s[14:15], 0, v[6:7]
	v_lshl_add_u64 v[6:7], v[6:7], 0, v[2:3]
	v_pk_mul_f32 v[244:245], v[110:111], s[98:99] op_sel_hi:[1,0]
	v_pk_mul_f32 v[234:235], v[110:111], s[98:99] op_sel:[0,1] op_sel_hi:[1,1]
	v_exp_f32_e32 v234, v234
	v_exp_f32_e32 v235, v235
	s_nop 0
	v_pk_add_f32 v[234:235], v[234:235], s[100:101] op_sel_hi:[1,0]
	v_rcp_f32_e32 v234, v234
	v_rcp_f32_e32 v235, v235
	s_nop 0
	v_pk_mul_f32 v[244:245], v[244:245], v[234:235]
	v_pk_mul_f32 v[244:245], v[244:245], v[106:107]
	global_store_dwordx2 v[6:7], v[8:9], off
	s_nop 0
	s_nop 0
	v_med3_f32 v5, v244, s10, v190
	s_nop 0
	v_pk_mul_f32 v[246:247], v[112:113], s[98:99] op_sel_hi:[1,0]
	v_pk_mul_f32 v[234:235], v[112:113], s[98:99] op_sel:[0,1] op_sel_hi:[1,1]
	v_exp_f32_e32 v234, v234
	v_exp_f32_e32 v235, v235
	s_nop 0
	v_pk_add_f32 v[234:235], v[234:235], s[100:101] op_sel_hi:[1,0]
	v_rcp_f32_e32 v234, v234
	v_rcp_f32_e32 v235, v235
	s_nop 0
	v_pk_mul_f32 v[246:247], v[246:247], v[234:235]
	v_pk_mul_f32 v[246:247], v[246:247], v[108:109]
	v_med3_f32 v7, v245, s10, v190
	s_nop 0
	s_nop 0
	s_nop 0
	v_pk_mul_f32 v[248:249], v[102:103], s[98:99] op_sel_hi:[1,0]
	v_pk_mul_f32 v[234:235], v[102:103], s[98:99] op_sel:[0,1] op_sel_hi:[1,1]
	v_exp_f32_e32 v234, v234
	v_exp_f32_e32 v235, v235
	s_nop 0
	v_pk_add_f32 v[234:235], v[234:235], s[100:101] op_sel_hi:[1,0]
	v_rcp_f32_e32 v234, v234
	v_rcp_f32_e32 v235, v235
	s_nop 0
	v_pk_mul_f32 v[248:249], v[248:249], v[234:235]
	v_pk_mul_f32 v[248:249], v[248:249], v[98:99]
	s_nop 0
	s_nop 0
	s_nop 0
	s_nop 0
	v_pk_mul_f32 v[250:251], v[104:105], s[98:99] op_sel_hi:[1,0]
	v_pk_mul_f32 v[234:235], v[104:105], s[98:99] op_sel:[0,1] op_sel_hi:[1,1]
	v_exp_f32_e32 v234, v234
	v_exp_f32_e32 v235, v235
	s_nop 0
	v_pk_add_f32 v[234:235], v[234:235], s[100:101] op_sel_hi:[1,0]
	v_rcp_f32_e32 v234, v234
	v_rcp_f32_e32 v235, v235
	s_nop 0
	v_pk_mul_f32 v[250:251], v[250:251], v[234:235]
	v_pk_mul_f32 v[250:251], v[250:251], v[100:101]
	s_nop 0
	s_nop 0
	s_nop 0
	s_nop 0
	v_mov_b32_e32 v8, v163
	v_cvt_pk_fp8_f32 v8, v5, v7
	v_med3_f32 v5, v246, s10, v190
	v_med3_f32 v7, v247, s10, v190
	v_mov_b32_e32 v9, v163
	v_cvt_pk_fp8_f32 v8, v5, v7 op_sel:[0,0,1]
	v_med3_f32 v5, v248, s10, v190
	v_med3_f32 v7, v249, s10, v190
	v_cvt_pk_fp8_f32 v9, v5, v7
	v_add_u32_e32 v6, 48, v4
	v_med3_f32 v5, v250, s10, v190
	v_med3_f32 v7, v251, s10, v190
	v_cvt_pk_fp8_f32 v9, v5, v7 op_sel:[0,0,1]
	v_ashrrev_i32_e32 v7, 31, v6
	v_lshlrev_b64 v[6:7], 7, v[6:7]
	v_lshl_add_u64 v[6:7], s[14:15], 0, v[6:7]
	v_lshl_add_u64 v[6:7], v[6:7], 0, v[2:3]
	v_pk_mul_f32 v[236:237], v[94:95], s[98:99] op_sel_hi:[1,0]
	v_pk_mul_f32 v[234:235], v[94:95], s[98:99] op_sel:[0,1] op_sel_hi:[1,1]
	v_exp_f32_e32 v234, v234
	v_exp_f32_e32 v235, v235
	s_nop 0
	v_pk_add_f32 v[234:235], v[234:235], s[100:101] op_sel_hi:[1,0]
	v_rcp_f32_e32 v234, v234
	v_rcp_f32_e32 v235, v235
	s_nop 0
	v_pk_mul_f32 v[236:237], v[236:237], v[234:235]
	v_pk_mul_f32 v[236:237], v[236:237], v[90:91]
	global_store_dwordx2 v[6:7], v[8:9], off
	v_add_u32_e32 v6, 0x80, v4
	s_nop 0
	v_med3_f32 v5, v236, s10, v190
	s_nop 0
	v_pk_mul_f32 v[238:239], v[96:97], s[98:99] op_sel_hi:[1,0]
	v_pk_mul_f32 v[234:235], v[96:97], s[98:99] op_sel:[0,1] op_sel_hi:[1,1]
	v_exp_f32_e32 v234, v234
	v_exp_f32_e32 v235, v235
	s_nop 0
	v_pk_add_f32 v[234:235], v[234:235], s[100:101] op_sel_hi:[1,0]
	v_rcp_f32_e32 v234, v234
	v_rcp_f32_e32 v235, v235
	s_nop 0
	v_pk_mul_f32 v[238:239], v[238:239], v[234:235]
	v_pk_mul_f32 v[238:239], v[238:239], v[92:93]
	v_med3_f32 v7, v237, s10, v190
	s_nop 0
	s_nop 0
	s_nop 0
	v_pk_mul_f32 v[240:241], v[86:87], s[98:99] op_sel_hi:[1,0]
	v_pk_mul_f32 v[234:235], v[86:87], s[98:99] op_sel:[0,1] op_sel_hi:[1,1]
	v_exp_f32_e32 v234, v234
	v_exp_f32_e32 v235, v235
	s_nop 0
	v_pk_add_f32 v[234:235], v[234:235], s[100:101] op_sel_hi:[1,0]
	v_rcp_f32_e32 v234, v234
	v_rcp_f32_e32 v235, v235
	s_nop 0
	v_pk_mul_f32 v[240:241], v[240:241], v[234:235]
	v_pk_mul_f32 v[240:241], v[240:241], v[82:83]
	s_nop 0
	s_nop 0
	s_nop 0
	s_nop 0
	v_pk_mul_f32 v[242:243], v[88:89], s[98:99] op_sel_hi:[1,0]
	v_pk_mul_f32 v[234:235], v[88:89], s[98:99] op_sel:[0,1] op_sel_hi:[1,1]
	v_exp_f32_e32 v234, v234
	v_exp_f32_e32 v235, v235
	s_nop 0
	v_pk_add_f32 v[234:235], v[234:235], s[100:101] op_sel_hi:[1,0]
	v_rcp_f32_e32 v234, v234
	v_rcp_f32_e32 v235, v235
	s_nop 0
	v_pk_mul_f32 v[242:243], v[242:243], v[234:235]
	v_pk_mul_f32 v[242:243], v[242:243], v[84:85]
	s_nop 0
	s_nop 0
	s_nop 0
	s_nop 0
	v_mov_b32_e32 v8, v163
	v_cvt_pk_fp8_f32 v8, v5, v7
	v_med3_f32 v5, v238, s10, v190
	v_med3_f32 v7, v239, s10, v190
	v_mov_b32_e32 v9, v163
	v_cvt_pk_fp8_f32 v8, v5, v7 op_sel:[0,0,1]
	v_med3_f32 v5, v240, s10, v190
	v_med3_f32 v7, v241, s10, v190
	v_cvt_pk_fp8_f32 v9, v5, v7
	v_med3_f32 v5, v242, s10, v190
	v_med3_f32 v7, v243, s10, v190
	v_cvt_pk_fp8_f32 v9, v5, v7 op_sel:[0,0,1]
	v_ashrrev_i32_e32 v7, 31, v6
	v_lshlrev_b64 v[6:7], 7, v[6:7]
	v_lshl_add_u64 v[6:7], s[14:15], 0, v[6:7]
	v_lshl_add_u64 v[6:7], v[6:7], 0, v[2:3]
	v_pk_mul_f32 v[244:245], v[78:79], s[98:99] op_sel_hi:[1,0]
	v_pk_mul_f32 v[234:235], v[78:79], s[98:99] op_sel:[0,1] op_sel_hi:[1,1]
	v_exp_f32_e32 v234, v234
	v_exp_f32_e32 v235, v235
	s_nop 0
	v_pk_add_f32 v[234:235], v[234:235], s[100:101] op_sel_hi:[1,0]
	v_rcp_f32_e32 v234, v234
	v_rcp_f32_e32 v235, v235
	s_nop 0
	v_pk_mul_f32 v[244:245], v[244:245], v[234:235]
	v_pk_mul_f32 v[244:245], v[244:245], v[74:75]
	global_store_dwordx2 v[6:7], v[8:9], off
	s_nop 0
	s_nop 0
	v_med3_f32 v5, v244, s10, v190
	s_nop 0
	v_pk_mul_f32 v[246:247], v[80:81], s[98:99] op_sel_hi:[1,0]
	v_pk_mul_f32 v[234:235], v[80:81], s[98:99] op_sel:[0,1] op_sel_hi:[1,1]
	v_exp_f32_e32 v234, v234
	v_exp_f32_e32 v235, v235
	s_nop 0
	v_pk_add_f32 v[234:235], v[234:235], s[100:101] op_sel_hi:[1,0]
	v_rcp_f32_e32 v234, v234
	v_rcp_f32_e32 v235, v235
	s_nop 0
	v_pk_mul_f32 v[246:247], v[246:247], v[234:235]
	v_pk_mul_f32 v[246:247], v[246:247], v[76:77]
	v_med3_f32 v7, v245, s10, v190
	s_nop 0
	s_nop 0
	s_nop 0
	v_pk_mul_f32 v[248:249], v[70:71], s[98:99] op_sel_hi:[1,0]
	v_pk_mul_f32 v[234:235], v[70:71], s[98:99] op_sel:[0,1] op_sel_hi:[1,1]
	v_exp_f32_e32 v234, v234
	v_exp_f32_e32 v235, v235
	s_nop 0
	v_pk_add_f32 v[234:235], v[234:235], s[100:101] op_sel_hi:[1,0]
	v_rcp_f32_e32 v234, v234
	v_rcp_f32_e32 v235, v235
	s_nop 0
	v_pk_mul_f32 v[248:249], v[248:249], v[234:235]
	v_pk_mul_f32 v[248:249], v[248:249], v[66:67]
	s_nop 0
	s_nop 0
	s_nop 0
	s_nop 0
	v_pk_mul_f32 v[250:251], v[72:73], s[98:99] op_sel_hi:[1,0]
	v_pk_mul_f32 v[234:235], v[72:73], s[98:99] op_sel:[0,1] op_sel_hi:[1,1]
	v_exp_f32_e32 v234, v234
	v_exp_f32_e32 v235, v235
	s_nop 0
	v_pk_add_f32 v[234:235], v[234:235], s[100:101] op_sel_hi:[1,0]
	v_rcp_f32_e32 v234, v234
	v_rcp_f32_e32 v235, v235
	s_nop 0
	v_pk_mul_f32 v[250:251], v[250:251], v[234:235]
	v_pk_mul_f32 v[250:251], v[250:251], v[68:69]
	s_nop 0
	s_nop 0
	s_nop 0
	s_nop 0
	v_mov_b32_e32 v8, v163
	v_cvt_pk_fp8_f32 v8, v5, v7
	v_med3_f32 v5, v246, s10, v190
	v_med3_f32 v7, v247, s10, v190
	v_mov_b32_e32 v9, v163
	v_cvt_pk_fp8_f32 v8, v5, v7 op_sel:[0,0,1]
	v_med3_f32 v5, v248, s10, v190
	v_med3_f32 v7, v249, s10, v190
	v_cvt_pk_fp8_f32 v9, v5, v7
	v_add_u32_e32 v6, 0x90, v4
	v_med3_f32 v5, v250, s10, v190
	v_med3_f32 v7, v251, s10, v190
	v_cvt_pk_fp8_f32 v9, v5, v7 op_sel:[0,0,1]
	v_ashrrev_i32_e32 v7, 31, v6
	v_lshlrev_b64 v[6:7], 7, v[6:7]
	v_lshl_add_u64 v[6:7], s[14:15], 0, v[6:7]
	v_lshl_add_u64 v[6:7], v[6:7], 0, v[2:3]
	v_pk_mul_f32 v[236:237], v[62:63], s[98:99] op_sel_hi:[1,0]
	v_pk_mul_f32 v[234:235], v[62:63], s[98:99] op_sel:[0,1] op_sel_hi:[1,1]
	v_exp_f32_e32 v234, v234
	v_exp_f32_e32 v235, v235
	s_nop 0
	v_pk_add_f32 v[234:235], v[234:235], s[100:101] op_sel_hi:[1,0]
	v_rcp_f32_e32 v234, v234
	v_rcp_f32_e32 v235, v235
	s_nop 0
	v_pk_mul_f32 v[236:237], v[236:237], v[234:235]
	v_pk_mul_f32 v[236:237], v[236:237], v[58:59]
	global_store_dwordx2 v[6:7], v[8:9], off
	s_nop 0
	s_nop 0
	v_med3_f32 v5, v236, s10, v190
	s_nop 0
	v_pk_mul_f32 v[238:239], v[64:65], s[98:99] op_sel_hi:[1,0]
	v_pk_mul_f32 v[234:235], v[64:65], s[98:99] op_sel:[0,1] op_sel_hi:[1,1]
	v_exp_f32_e32 v234, v234
	v_exp_f32_e32 v235, v235
	s_nop 0
	v_pk_add_f32 v[234:235], v[234:235], s[100:101] op_sel_hi:[1,0]
	v_rcp_f32_e32 v234, v234
	v_rcp_f32_e32 v235, v235
	s_nop 0
	v_pk_mul_f32 v[238:239], v[238:239], v[234:235]
	v_pk_mul_f32 v[238:239], v[238:239], v[60:61]
	v_med3_f32 v7, v237, s10, v190
	s_nop 0
	s_nop 0
	s_nop 0
	v_pk_mul_f32 v[240:241], v[54:55], s[98:99] op_sel_hi:[1,0]
	v_pk_mul_f32 v[234:235], v[54:55], s[98:99] op_sel:[0,1] op_sel_hi:[1,1]
	v_exp_f32_e32 v234, v234
	v_exp_f32_e32 v235, v235
	s_nop 0
	v_pk_add_f32 v[234:235], v[234:235], s[100:101] op_sel_hi:[1,0]
	v_rcp_f32_e32 v234, v234
	v_rcp_f32_e32 v235, v235
	s_nop 0
	v_pk_mul_f32 v[240:241], v[240:241], v[234:235]
	v_pk_mul_f32 v[240:241], v[240:241], v[50:51]
	s_nop 0
	s_nop 0
	s_nop 0
	s_nop 0
	v_pk_mul_f32 v[242:243], v[56:57], s[98:99] op_sel_hi:[1,0]
	v_pk_mul_f32 v[234:235], v[56:57], s[98:99] op_sel:[0,1] op_sel_hi:[1,1]
	v_exp_f32_e32 v234, v234
	v_exp_f32_e32 v235, v235
	s_nop 0
	v_pk_add_f32 v[234:235], v[234:235], s[100:101] op_sel_hi:[1,0]
	v_rcp_f32_e32 v234, v234
	v_rcp_f32_e32 v235, v235
	s_nop 0
	v_pk_mul_f32 v[242:243], v[242:243], v[234:235]
	v_pk_mul_f32 v[242:243], v[242:243], v[52:53]
	s_nop 0
	s_nop 0
	s_nop 0
	s_nop 0
	v_mov_b32_e32 v8, v163
	v_cvt_pk_fp8_f32 v8, v5, v7
	v_med3_f32 v5, v238, s10, v190
	v_med3_f32 v7, v239, s10, v190
	v_mov_b32_e32 v9, v163
	v_cvt_pk_fp8_f32 v8, v5, v7 op_sel:[0,0,1]
	v_med3_f32 v5, v240, s10, v190
	v_med3_f32 v7, v241, s10, v190
	v_cvt_pk_fp8_f32 v9, v5, v7
	v_add_u32_e32 v6, 0xa0, v4
	v_med3_f32 v5, v242, s10, v190
	v_med3_f32 v7, v243, s10, v190
	v_cvt_pk_fp8_f32 v9, v5, v7 op_sel:[0,0,1]
	v_ashrrev_i32_e32 v7, 31, v6
	v_lshlrev_b64 v[6:7], 7, v[6:7]
	v_lshl_add_u64 v[6:7], s[14:15], 0, v[6:7]
	v_lshl_add_u64 v[6:7], v[6:7], 0, v[2:3]
	v_pk_mul_f32 v[244:245], v[46:47], s[98:99] op_sel_hi:[1,0]
	v_pk_mul_f32 v[234:235], v[46:47], s[98:99] op_sel:[0,1] op_sel_hi:[1,1]
	v_exp_f32_e32 v234, v234
	v_exp_f32_e32 v235, v235
	s_nop 0
	v_pk_add_f32 v[234:235], v[234:235], s[100:101] op_sel_hi:[1,0]
	v_rcp_f32_e32 v234, v234
	v_rcp_f32_e32 v235, v235
	s_nop 0
	v_pk_mul_f32 v[244:245], v[244:245], v[234:235]
	v_pk_mul_f32 v[244:245], v[244:245], v[42:43]
	global_store_dwordx2 v[6:7], v[8:9], off
	v_add_u32_e32 v4, 0xb0, v4
	s_nop 0
	v_med3_f32 v5, v244, s10, v190
	s_nop 0
	v_pk_mul_f32 v[246:247], v[48:49], s[98:99] op_sel_hi:[1,0]
	v_pk_mul_f32 v[234:235], v[48:49], s[98:99] op_sel:[0,1] op_sel_hi:[1,1]
	v_exp_f32_e32 v234, v234
	v_exp_f32_e32 v235, v235
	s_nop 0
	v_pk_add_f32 v[234:235], v[234:235], s[100:101] op_sel_hi:[1,0]
	v_rcp_f32_e32 v234, v234
	v_rcp_f32_e32 v235, v235
	s_nop 0
	v_pk_mul_f32 v[246:247], v[246:247], v[234:235]
	v_pk_mul_f32 v[246:247], v[246:247], v[44:45]
	s_nop 0
	s_nop 0
	v_pk_mul_f32 v[248:249], v[38:39], s[98:99] op_sel_hi:[1,0]
	v_pk_mul_f32 v[234:235], v[38:39], s[98:99] op_sel:[0,1] op_sel_hi:[1,1]
	v_exp_f32_e32 v234, v234
	v_exp_f32_e32 v235, v235
	s_nop 0
	v_pk_add_f32 v[234:235], v[234:235], s[100:101] op_sel_hi:[1,0]
	v_rcp_f32_e32 v234, v234
	v_rcp_f32_e32 v235, v235
	s_nop 0
	v_pk_mul_f32 v[248:249], v[248:249], v[234:235]
	v_pk_mul_f32 v[248:249], v[248:249], v[34:35]
	s_nop 0
	s_nop 0
	v_pk_mul_f32 v[250:251], v[40:41], s[98:99] op_sel_hi:[1,0]
	v_pk_mul_f32 v[234:235], v[40:41], s[98:99] op_sel:[0,1] op_sel_hi:[1,1]
	v_exp_f32_e32 v234, v234
	v_exp_f32_e32 v235, v235
	s_nop 0
	v_pk_add_f32 v[234:235], v[234:235], s[100:101] op_sel_hi:[1,0]
	v_rcp_f32_e32 v234, v234
	v_rcp_f32_e32 v235, v235
	s_nop 0
	v_pk_mul_f32 v[250:251], v[250:251], v[234:235]
	v_pk_mul_f32 v[250:251], v[250:251], v[36:37]
	s_nop 0
	s_nop 0
	v_med3_f32 v13, v245, s10, v190
	v_mov_b32_e32 v6, v163
	v_cvt_pk_fp8_f32 v6, v5, v13
	v_med3_f32 v5, v246, s10, v190
	v_med3_f32 v7, v247, s10, v190
	v_med3_f32 v8, v249, s10, v190
	v_cvt_pk_fp8_f32 v6, v5, v7 op_sel:[0,0,1]
	v_med3_f32 v5, v248, s10, v190
	v_mov_b32_e32 v7, v163
	v_cvt_pk_fp8_f32 v7, v5, v8
	v_med3_f32 v5, v250, s10, v190
	v_med3_f32 v8, v251, s10, v190
	v_cvt_pk_fp8_f32 v7, v5, v8 op_sel:[0,0,1]
	v_ashrrev_i32_e32 v5, 31, v4
	v_lshlrev_b64 v[4:5], 7, v[4:5]
	v_lshl_add_u64 v[4:5], s[14:15], 0, v[4:5]
	v_lshl_add_u64 v[2:3], v[4:5], 0, v[2:3]
	global_store_dwordx2 v[2:3], v[6:7], off
	s_cbranch_vccz .LBB0_2030
	s_waitcnt vmcnt(0)
	s_cmpk_gt_u32 s42, 0xff
	s_cbranch_scc1 .LBB0_1976
	s_barrier
	s_branch .LBB0_1976

.Lpeel_exit_17:
	s_mov_b32 s98, 0x3b000000
	s_mov_b32 s99, 0xbcb8aa3b
	s_mov_b32 s100, 1.0
	v_pk_mul_f32 v[236:237], v[158:159], s[98:99] op_sel_hi:[1,0]
	v_pk_mul_f32 v[234:235], v[158:159], s[98:99] op_sel:[0,1] op_sel_hi:[1,1]
	v_exp_f32_e32 v234, v234
	v_exp_f32_e32 v235, v235
	s_nop 0
	v_pk_add_f32 v[234:235], v[234:235], s[100:101] op_sel_hi:[1,0]
	v_rcp_f32_e32 v234, v234
	v_rcp_f32_e32 v235, v235
	s_nop 0
	v_pk_mul_f32 v[236:237], v[236:237], v[234:235]
	v_pk_mul_f32 v[236:237], v[236:237], v[154:155]
	s_ashr_i32 s29, s28, 31
	s_ashr_i32 s27, s26, 31
	s_lshl_b64 s[10:11], s[28:29], 18
	s_lshl_b64 s[26:27], s[26:27], 15
	v_mov_b32_e32 v3, v194
	s_add_u32 s0, s8, s10
	v_med3_f32 v5, v236, s40, v189
	s_nop 15
	s_nop 15
	v_mov_b32_e32 v2, v195
	v_pk_mul_f32 v[238:239], v[160:161], s[98:99] op_sel_hi:[1,0]
	v_pk_mul_f32 v[234:235], v[160:161], s[98:99] op_sel:[0,1] op_sel_hi:[1,1]
	v_exp_f32_e32 v234, v234
	v_exp_f32_e32 v235, v235
	s_nop 0
	v_pk_add_f32 v[234:235], v[234:235], s[100:101] op_sel_hi:[1,0]
	v_rcp_f32_e32 v234, v234
	v_rcp_f32_e32 v235, v235
	s_nop 0
	v_pk_mul_f32 v[238:239], v[238:239], v[234:235]
	v_pk_mul_f32 v[238:239], v[238:239], v[156:157]
	v_add_u32_e32 v4, s49, v3
	s_addc_u32 s1, s9, s11
	s_add_u32 s10, s0, s26
	v_lshl_add_u32 v2, v2, 3, s50
	s_addc_u32 s11, s1, s27
	v_ashrrev_i32_e32 v3, 31, v2
	s_and_b64 vcc, exec, s[6:7]
	v_pk_mul_f32 v[240:241], v[150:151], s[98:99] op_sel_hi:[1,0]
	v_pk_mul_f32 v[234:235], v[150:151], s[98:99] op_sel:[0,1] op_sel_hi:[1,1]
	v_exp_f32_e32 v234, v234
	v_exp_f32_e32 v235, v235
	s_nop 0
	v_pk_add_f32 v[234:235], v[234:235], s[100:101] op_sel_hi:[1,0]
	v_rcp_f32_e32 v234, v234
	v_rcp_f32_e32 v235, v235
	s_nop 0
	v_pk_mul_f32 v[240:241], v[240:241], v[234:235]
	v_pk_mul_f32 v[240:241], v[240:241], v[146:147]
	v_mov_b32_e32 v174, v199
	v_mov_b32_e32 v172, v198
	v_mov_b32_e32 v170, v197
	v_mov_b32_e32 v168, v171
	s_mov_b32 s26, s24
	s_mov_b32 s28, s54
	s_mov_b64 s[30:31], s[12:13]
	v_pk_mul_f32 v[242:243], v[152:153], s[98:99] op_sel_hi:[1,0]
	v_pk_mul_f32 v[234:235], v[152:153], s[98:99] op_sel:[0,1] op_sel_hi:[1,1]
	v_exp_f32_e32 v234, v234
	v_exp_f32_e32 v235, v235
	s_nop 0
	v_pk_add_f32 v[234:235], v[234:235], s[100:101] op_sel_hi:[1,0]
	v_rcp_f32_e32 v234, v234
	v_rcp_f32_e32 v235, v235
	s_nop 0
	v_pk_mul_f32 v[242:243], v[242:243], v[234:235]
	v_pk_mul_f32 v[242:243], v[242:243], v[148:149]
	s_nop 0
	s_nop 0
	v_med3_f32 v13, v237, s40, v189
	v_mov_b32_e32 v6, v163
	v_cvt_pk_fp8_f32 v6, v5, v13
	v_med3_f32 v5, v238, s40, v189
	v_med3_f32 v7, v239, s40, v189
	v_med3_f32 v8, v241, s40, v189
	v_cvt_pk_fp8_f32 v6, v5, v7 op_sel:[0,0,1]
	v_med3_f32 v5, v240, s40, v189
	v_mov_b32_e32 v7, v163
	v_cvt_pk_fp8_f32 v7, v5, v8
	v_med3_f32 v5, v242, s40, v189
	v_med3_f32 v8, v243, s40, v189
	v_cvt_pk_fp8_f32 v7, v5, v8 op_sel:[0,0,1]
	v_ashrrev_i32_e32 v5, 31, v4
	v_lshlrev_b64 v[8:9], 7, v[4:5]
	v_lshl_add_u64 v[8:9], s[10:11], 0, v[8:9]
	v_lshl_add_u64 v[8:9], v[8:9], 0, v[2:3]
	v_pk_mul_f32 v[244:245], v[142:143], s[98:99] op_sel_hi:[1,0]
	v_pk_mul_f32 v[234:235], v[142:143], s[98:99] op_sel:[0,1] op_sel_hi:[1,1]
	v_exp_f32_e32 v234, v234
	v_exp_f32_e32 v235, v235
	s_nop 0
	v_pk_add_f32 v[234:235], v[234:235], s[100:101] op_sel_hi:[1,0]
	v_rcp_f32_e32 v234, v234
	v_rcp_f32_e32 v235, v235
	s_nop 0
	v_pk_mul_f32 v[244:245], v[244:245], v[234:235]
	v_pk_mul_f32 v[244:245], v[244:245], v[138:139]
	global_store_dwordx2 v[8:9], v[6:7], off
	s_nop 0
	s_nop 0
	v_med3_f32 v5, v244, s40, v189
	s_nop 0
	v_pk_mul_f32 v[246:247], v[144:145], s[98:99] op_sel_hi:[1,0]
	v_pk_mul_f32 v[234:235], v[144:145], s[98:99] op_sel:[0,1] op_sel_hi:[1,1]
	v_exp_f32_e32 v234, v234
	v_exp_f32_e32 v235, v235
	s_nop 0
	v_pk_add_f32 v[234:235], v[234:235], s[100:101] op_sel_hi:[1,0]
	v_rcp_f32_e32 v234, v234
	v_rcp_f32_e32 v235, v235
	s_nop 0
	v_pk_mul_f32 v[246:247], v[246:247], v[234:235]
	v_pk_mul_f32 v[246:247], v[246:247], v[140:141]
	v_med3_f32 v7, v245, s40, v189
	s_nop 0
	s_nop 0
	s_nop 0
	v_pk_mul_f32 v[248:249], v[134:135], s[98:99] op_sel_hi:[1,0]
	v_pk_mul_f32 v[234:235], v[134:135], s[98:99] op_sel:[0,1] op_sel_hi:[1,1]
	v_exp_f32_e32 v234, v234
	v_exp_f32_e32 v235, v235
	s_nop 0
	v_pk_add_f32 v[234:235], v[234:235], s[100:101] op_sel_hi:[1,0]
	v_rcp_f32_e32 v234, v234
	v_rcp_f32_e32 v235, v235
	s_nop 0
	v_pk_mul_f32 v[248:249], v[248:249], v[234:235]
	v_pk_mul_f32 v[248:249], v[248:249], v[130:131]
	s_nop 0
	s_nop 0
	s_nop 0
	s_nop 0
	v_pk_mul_f32 v[250:251], v[136:137], s[98:99] op_sel_hi:[1,0]
	v_pk_mul_f32 v[234:235], v[136:137], s[98:99] op_sel:[0,1] op_sel_hi:[1,1]
	v_exp_f32_e32 v234, v234
	v_exp_f32_e32 v235, v235
	s_nop 0
	v_pk_add_f32 v[234:235], v[234:235], s[100:101] op_sel_hi:[1,0]
	v_rcp_f32_e32 v234, v234
	v_rcp_f32_e32 v235, v235
	s_nop 0
	v_pk_mul_f32 v[250:251], v[250:251], v[234:235]
	v_pk_mul_f32 v[250:251], v[250:251], v[132:133]
	s_nop 0
	s_nop 0
	s_nop 0
	s_nop 0
	v_mov_b32_e32 v8, v163
	v_cvt_pk_fp8_f32 v8, v5, v7
	v_med3_f32 v5, v246, s40, v189
	v_med3_f32 v7, v247, s40, v189
	v_mov_b32_e32 v9, v163
	v_cvt_pk_fp8_f32 v8, v5, v7 op_sel:[0,0,1]
	v_med3_f32 v5, v248, s40, v189
	v_med3_f32 v7, v249, s40, v189
	v_cvt_pk_fp8_f32 v9, v5, v7
	v_add_u32_e32 v6, 16, v4
	v_med3_f32 v5, v250, s40, v189
	v_med3_f32 v7, v251, s40, v189
	v_cvt_pk_fp8_f32 v9, v5, v7 op_sel:[0,0,1]
	v_ashrrev_i32_e32 v7, 31, v6
	v_lshlrev_b64 v[6:7], 7, v[6:7]
	v_lshl_add_u64 v[6:7], s[10:11], 0, v[6:7]
	v_lshl_add_u64 v[6:7], v[6:7], 0, v[2:3]
	v_pk_mul_f32 v[236:237], v[126:127], s[98:99] op_sel_hi:[1,0]
	v_pk_mul_f32 v[234:235], v[126:127], s[98:99] op_sel:[0,1] op_sel_hi:[1,1]
	v_exp_f32_e32 v234, v234
	v_exp_f32_e32 v235, v235
	s_nop 0
	v_pk_add_f32 v[234:235], v[234:235], s[100:101] op_sel_hi:[1,0]
	v_rcp_f32_e32 v234, v234
	v_rcp_f32_e32 v235, v235
	s_nop 0
	v_pk_mul_f32 v[236:237], v[236:237], v[234:235]
	v_pk_mul_f32 v[236:237], v[236:237], v[122:123]
	global_store_dwordx2 v[6:7], v[8:9], off
	s_nop 0
	s_nop 0
	v_med3_f32 v5, v236, s40, v189
	s_nop 0
	v_pk_mul_f32 v[238:239], v[128:129], s[98:99] op_sel_hi:[1,0]
	v_pk_mul_f32 v[234:235], v[128:129], s[98:99] op_sel:[0,1] op_sel_hi:[1,1]
	v_exp_f32_e32 v234, v234
	v_exp_f32_e32 v235, v235
	s_nop 0
	v_pk_add_f32 v[234:235], v[234:235], s[100:101] op_sel_hi:[1,0]
	v_rcp_f32_e32 v234, v234
	v_rcp_f32_e32 v235, v235
	s_nop 0
	v_pk_mul_f32 v[238:239], v[238:239], v[234:235]
	v_pk_mul_f32 v[238:239], v[238:239], v[124:125]
	v_med3_f32 v7, v237, s40, v189
	s_nop 0
	s_nop 0
	s_nop 0
	v_pk_mul_f32 v[240:241], v[118:119], s[98:99] op_sel_hi:[1,0]
	v_pk_mul_f32 v[234:235], v[118:119], s[98:99] op_sel:[0,1] op_sel_hi:[1,1]
	v_exp_f32_e32 v234, v234
	v_exp_f32_e32 v235, v235
	s_nop 0
	v_pk_add_f32 v[234:235], v[234:235], s[100:101] op_sel_hi:[1,0]
	v_rcp_f32_e32 v234, v234
	v_rcp_f32_e32 v235, v235
	s_nop 0
	v_pk_mul_f32 v[240:241], v[240:241], v[234:235]
	v_pk_mul_f32 v[240:241], v[240:241], v[114:115]
	s_nop 0
	s_nop 0
	s_nop 0
	s_nop 0
	v_pk_mul_f32 v[242:243], v[120:121], s[98:99] op_sel_hi:[1,0]
	v_pk_mul_f32 v[234:235], v[120:121], s[98:99] op_sel:[0,1] op_sel_hi:[1,1]
	v_exp_f32_e32 v234, v234
	v_exp_f32_e32 v235, v235
	s_nop 0
	v_pk_add_f32 v[234:235], v[234:235], s[100:101] op_sel_hi:[1,0]
	v_rcp_f32_e32 v234, v234
	v_rcp_f32_e32 v235, v235
	s_nop 0
	v_pk_mul_f32 v[242:243], v[242:243], v[234:235]
	v_pk_mul_f32 v[242:243], v[242:243], v[116:117]
	s_nop 0
	s_nop 0
	s_nop 0
	s_nop 0
	v_mov_b32_e32 v8, v163
	v_cvt_pk_fp8_f32 v8, v5, v7
	v_med3_f32 v5, v238, s40, v189
	v_med3_f32 v7, v239, s40, v189
	v_mov_b32_e32 v9, v163
	v_cvt_pk_fp8_f32 v8, v5, v7 op_sel:[0,0,1]
	v_med3_f32 v5, v240, s40, v189
	v_med3_f32 v7, v241, s40, v189
	v_cvt_pk_fp8_f32 v9, v5, v7
	v_add_u32_e32 v6, 32, v4
	v_med3_f32 v5, v242, s40, v189
	v_med3_f32 v7, v243, s40, v189
	v_cvt_pk_fp8_f32 v9, v5, v7 op_sel:[0,0,1]
	v_ashrrev_i32_e32 v7, 31, v6
	v_lshlrev_b64 v[6:7], 7, v[6:7]
	v_lshl_add_u64 v[6:7], s[10:11], 0, v[6:7]
	v_lshl_add_u64 v[6:7], v[6:7], 0, v[2:3]
	v_pk_mul_f32 v[244:245], v[110:111], s[98:99] op_sel_hi:[1,0]
	v_pk_mul_f32 v[234:235], v[110:111], s[98:99] op_sel:[0,1] op_sel_hi:[1,1]
	v_exp_f32_e32 v234, v234
	v_exp_f32_e32 v235, v235
	s_nop 0
	v_pk_add_f32 v[234:235], v[234:235], s[100:101] op_sel_hi:[1,0]
	v_rcp_f32_e32 v234, v234
	v_rcp_f32_e32 v235, v235
	s_nop 0
	v_pk_mul_f32 v[244:245], v[244:245], v[234:235]
	v_pk_mul_f32 v[244:245], v[244:245], v[106:107]
	global_store_dwordx2 v[6:7], v[8:9], off
	s_nop 0
	s_nop 0
	v_med3_f32 v5, v244, s40, v189
	s_nop 0
	v_pk_mul_f32 v[246:247], v[112:113], s[98:99] op_sel_hi:[1,0]
	v_pk_mul_f32 v[234:235], v[112:113], s[98:99] op_sel:[0,1] op_sel_hi:[1,1]
	v_exp_f32_e32 v234, v234
	v_exp_f32_e32 v235, v235
	s_nop 0
	v_pk_add_f32 v[234:235], v[234:235], s[100:101] op_sel_hi:[1,0]
	v_rcp_f32_e32 v234, v234
	v_rcp_f32_e32 v235, v235
	s_nop 0
	v_pk_mul_f32 v[246:247], v[246:247], v[234:235]
	v_pk_mul_f32 v[246:247], v[246:247], v[108:109]
	v_med3_f32 v7, v245, s40, v189
	s_nop 0
	s_nop 0
	s_nop 0
	v_pk_mul_f32 v[248:249], v[102:103], s[98:99] op_sel_hi:[1,0]
	v_pk_mul_f32 v[234:235], v[102:103], s[98:99] op_sel:[0,1] op_sel_hi:[1,1]
	v_exp_f32_e32 v234, v234
	v_exp_f32_e32 v235, v235
	s_nop 0
	v_pk_add_f32 v[234:235], v[234:235], s[100:101] op_sel_hi:[1,0]
	v_rcp_f32_e32 v234, v234
	v_rcp_f32_e32 v235, v235
	s_nop 0
	v_pk_mul_f32 v[248:249], v[248:249], v[234:235]
	v_pk_mul_f32 v[248:249], v[248:249], v[98:99]
	s_nop 0
	s_nop 0
	s_nop 0
	s_nop 0
	v_pk_mul_f32 v[250:251], v[104:105], s[98:99] op_sel_hi:[1,0]
	v_pk_mul_f32 v[234:235], v[104:105], s[98:99] op_sel:[0,1] op_sel_hi:[1,1]
	v_exp_f32_e32 v234, v234
	v_exp_f32_e32 v235, v235
	s_nop 0
	v_pk_add_f32 v[234:235], v[234:235], s[100:101] op_sel_hi:[1,0]
	v_rcp_f32_e32 v234, v234
	v_rcp_f32_e32 v235, v235
	s_nop 0
	v_pk_mul_f32 v[250:251], v[250:251], v[234:235]
	v_pk_mul_f32 v[250:251], v[250:251], v[100:101]
	s_nop 0
	s_nop 0
	s_nop 0
	s_nop 0
	v_mov_b32_e32 v8, v163
	v_cvt_pk_fp8_f32 v8, v5, v7
	v_med3_f32 v5, v246, s40, v189
	v_med3_f32 v7, v247, s40, v189
	v_mov_b32_e32 v9, v163
	v_cvt_pk_fp8_f32 v8, v5, v7 op_sel:[0,0,1]
	v_med3_f32 v5, v248, s40, v189
	v_med3_f32 v7, v249, s40, v189
	v_cvt_pk_fp8_f32 v9, v5, v7
	v_add_u32_e32 v6, 48, v4
	v_med3_f32 v5, v250, s40, v189
	v_med3_f32 v7, v251, s40, v189
	v_cvt_pk_fp8_f32 v9, v5, v7 op_sel:[0,0,1]
	v_ashrrev_i32_e32 v7, 31, v6
	v_lshlrev_b64 v[6:7], 7, v[6:7]
	v_lshl_add_u64 v[6:7], s[10:11], 0, v[6:7]
	v_lshl_add_u64 v[6:7], v[6:7], 0, v[2:3]
	v_pk_mul_f32 v[236:237], v[94:95], s[98:99] op_sel_hi:[1,0]
	v_pk_mul_f32 v[234:235], v[94:95], s[98:99] op_sel:[0,1] op_sel_hi:[1,1]
	v_exp_f32_e32 v234, v234
	v_exp_f32_e32 v235, v235
	s_nop 0
	v_pk_add_f32 v[234:235], v[234:235], s[100:101] op_sel_hi:[1,0]
	v_rcp_f32_e32 v234, v234
	v_rcp_f32_e32 v235, v235
	s_nop 0
	v_pk_mul_f32 v[236:237], v[236:237], v[234:235]
	v_pk_mul_f32 v[236:237], v[236:237], v[90:91]
	global_store_dwordx2 v[6:7], v[8:9], off
	v_add_u32_e32 v6, 0x80, v4
	s_nop 0
	v_med3_f32 v5, v236, s40, v189
	s_nop 0
	v_pk_mul_f32 v[238:239], v[96:97], s[98:99] op_sel_hi:[1,0]
	v_pk_mul_f32 v[234:235], v[96:97], s[98:99] op_sel:[0,1] op_sel_hi:[1,1]
	v_exp_f32_e32 v234, v234
	v_exp_f32_e32 v235, v235
	s_nop 0
	v_pk_add_f32 v[234:235], v[234:235], s[100:101] op_sel_hi:[1,0]
	v_rcp_f32_e32 v234, v234
	v_rcp_f32_e32 v235, v235
	s_nop 0
	v_pk_mul_f32 v[238:239], v[238:239], v[234:235]
	v_pk_mul_f32 v[238:239], v[238:239], v[92:93]
	v_med3_f32 v7, v237, s40, v189
	s_nop 0
	s_nop 0
	s_nop 0
	v_pk_mul_f32 v[240:241], v[86:87], s[98:99] op_sel_hi:[1,0]
	v_pk_mul_f32 v[234:235], v[86:87], s[98:99] op_sel:[0,1] op_sel_hi:[1,1]
	v_exp_f32_e32 v234, v234
	v_exp_f32_e32 v235, v235
	s_nop 0
	v_pk_add_f32 v[234:235], v[234:235], s[100:101] op_sel_hi:[1,0]
	v_rcp_f32_e32 v234, v234
	v_rcp_f32_e32 v235, v235
	s_nop 0
	v_pk_mul_f32 v[240:241], v[240:241], v[234:235]
	v_pk_mul_f32 v[240:241], v[240:241], v[82:83]
	s_nop 0
	s_nop 0
	s_nop 0
	s_nop 0
	v_pk_mul_f32 v[242:243], v[88:89], s[98:99] op_sel_hi:[1,0]
	v_pk_mul_f32 v[234:235], v[88:89], s[98:99] op_sel:[0,1] op_sel_hi:[1,1]
	v_exp_f32_e32 v234, v234
	v_exp_f32_e32 v235, v235
	s_nop 0
	v_pk_add_f32 v[234:235], v[234:235], s[100:101] op_sel_hi:[1,0]
	v_rcp_f32_e32 v234, v234
	v_rcp_f32_e32 v235, v235
	s_nop 0
	v_pk_mul_f32 v[242:243], v[242:243], v[234:235]
	v_pk_mul_f32 v[242:243], v[242:243], v[84:85]
	s_nop 0
	s_nop 0
	s_nop 0
	s_nop 0
	v_mov_b32_e32 v8, v163
	v_cvt_pk_fp8_f32 v8, v5, v7
	v_med3_f32 v5, v238, s40, v189
	v_med3_f32 v7, v239, s40, v189
	v_mov_b32_e32 v9, v163
	v_cvt_pk_fp8_f32 v8, v5, v7 op_sel:[0,0,1]
	v_med3_f32 v5, v240, s40, v189
	v_med3_f32 v7, v241, s40, v189
	v_cvt_pk_fp8_f32 v9, v5, v7
	v_med3_f32 v5, v242, s40, v189
	v_med3_f32 v7, v243, s40, v189
	v_cvt_pk_fp8_f32 v9, v5, v7 op_sel:[0,0,1]
	v_ashrrev_i32_e32 v7, 31, v6
	v_lshlrev_b64 v[6:7], 7, v[6:7]
	v_lshl_add_u64 v[6:7], s[10:11], 0, v[6:7]
	v_lshl_add_u64 v[6:7], v[6:7], 0, v[2:3]
	v_pk_mul_f32 v[244:245], v[78:79], s[98:99] op_sel_hi:[1,0]
	v_pk_mul_f32 v[234:235], v[78:79], s[98:99] op_sel:[0,1] op_sel_hi:[1,1]
	v_exp_f32_e32 v234, v234
	v_exp_f32_e32 v235, v235
	s_nop 0
	v_pk_add_f32 v[234:235], v[234:235], s[100:101] op_sel_hi:[1,0]
	v_rcp_f32_e32 v234, v234
	v_rcp_f32_e32 v235, v235
	s_nop 0
	v_pk_mul_f32 v[244:245], v[244:245], v[234:235]
	v_pk_mul_f32 v[244:245], v[244:245], v[74:75]
	global_store_dwordx2 v[6:7], v[8:9], off
	s_nop 0
	s_nop 0
	v_med3_f32 v5, v244, s40, v189
	s_nop 0
	v_pk_mul_f32 v[246:247], v[80:81], s[98:99] op_sel_hi:[1,0]
	v_pk_mul_f32 v[234:235], v[80:81], s[98:99] op_sel:[0,1] op_sel_hi:[1,1]
	v_exp_f32_e32 v234, v234
	v_exp_f32_e32 v235, v235
	s_nop 0
	v_pk_add_f32 v[234:235], v[234:235], s[100:101] op_sel_hi:[1,0]
	v_rcp_f32_e32 v234, v234
	v_rcp_f32_e32 v235, v235
	s_nop 0
	v_pk_mul_f32 v[246:247], v[246:247], v[234:235]
	v_pk_mul_f32 v[246:247], v[246:247], v[76:77]
	v_med3_f32 v7, v245, s40, v189
	s_nop 0
	s_nop 0
	s_nop 0
	v_pk_mul_f32 v[248:249], v[70:71], s[98:99] op_sel_hi:[1,0]
	v_pk_mul_f32 v[234:235], v[70:71], s[98:99] op_sel:[0,1] op_sel_hi:[1,1]
	v_exp_f32_e32 v234, v234
	v_exp_f32_e32 v235, v235
	s_nop 0
	v_pk_add_f32 v[234:235], v[234:235], s[100:101] op_sel_hi:[1,0]
	v_rcp_f32_e32 v234, v234
	v_rcp_f32_e32 v235, v235
	s_nop 0
	v_pk_mul_f32 v[248:249], v[248:249], v[234:235]
	v_pk_mul_f32 v[248:249], v[248:249], v[66:67]
	s_nop 0
	s_nop 0
	s_nop 0
	s_nop 0
	v_pk_mul_f32 v[250:251], v[72:73], s[98:99] op_sel_hi:[1,0]
	v_pk_mul_f32 v[234:235], v[72:73], s[98:99] op_sel:[0,1] op_sel_hi:[1,1]
	v_exp_f32_e32 v234, v234
	v_exp_f32_e32 v235, v235
	s_nop 0
	v_pk_add_f32 v[234:235], v[234:235], s[100:101] op_sel_hi:[1,0]
	v_rcp_f32_e32 v234, v234
	v_rcp_f32_e32 v235, v235
	s_nop 0
	v_pk_mul_f32 v[250:251], v[250:251], v[234:235]
	v_pk_mul_f32 v[250:251], v[250:251], v[68:69]
	s_nop 0
	s_nop 0
	s_nop 0
	s_nop 0
	v_mov_b32_e32 v8, v163
	v_cvt_pk_fp8_f32 v8, v5, v7
	v_med3_f32 v5, v246, s40, v189
	v_med3_f32 v7, v247, s40, v189
	v_mov_b32_e32 v9, v163
	v_cvt_pk_fp8_f32 v8, v5, v7 op_sel:[0,0,1]
	v_med3_f32 v5, v248, s40, v189
	v_med3_f32 v7, v249, s40, v189
	v_cvt_pk_fp8_f32 v9, v5, v7
	v_add_u32_e32 v6, 0x90, v4
	v_med3_f32 v5, v250, s40, v189
	v_med3_f32 v7, v251, s40, v189
	v_cvt_pk_fp8_f32 v9, v5, v7 op_sel:[0,0,1]
	v_ashrrev_i32_e32 v7, 31, v6
	v_lshlrev_b64 v[6:7], 7, v[6:7]
	v_lshl_add_u64 v[6:7], s[10:11], 0, v[6:7]
	v_lshl_add_u64 v[6:7], v[6:7], 0, v[2:3]
	v_pk_mul_f32 v[236:237], v[62:63], s[98:99] op_sel_hi:[1,0]
	v_pk_mul_f32 v[234:235], v[62:63], s[98:99] op_sel:[0,1] op_sel_hi:[1,1]
	v_exp_f32_e32 v234, v234
	v_exp_f32_e32 v235, v235
	s_nop 0
	v_pk_add_f32 v[234:235], v[234:235], s[100:101] op_sel_hi:[1,0]
	v_rcp_f32_e32 v234, v234
	v_rcp_f32_e32 v235, v235
	s_nop 0
	v_pk_mul_f32 v[236:237], v[236:237], v[234:235]
	v_pk_mul_f32 v[236:237], v[236:237], v[58:59]
	global_store_dwordx2 v[6:7], v[8:9], off
	s_nop 0
	s_nop 0
	v_med3_f32 v5, v236, s40, v189
	s_nop 0
	v_pk_mul_f32 v[238:239], v[64:65], s[98:99] op_sel_hi:[1,0]
	v_pk_mul_f32 v[234:235], v[64:65], s[98:99] op_sel:[0,1] op_sel_hi:[1,1]
	v_exp_f32_e32 v234, v234
	v_exp_f32_e32 v235, v235
	s_nop 0
	v_pk_add_f32 v[234:235], v[234:235], s[100:101] op_sel_hi:[1,0]
	v_rcp_f32_e32 v234, v234
	v_rcp_f32_e32 v235, v235
	s_nop 0
	v_pk_mul_f32 v[238:239], v[238:239], v[234:235]
	v_pk_mul_f32 v[238:239], v[238:239], v[60:61]
	v_med3_f32 v7, v237, s40, v189
	s_nop 0
	s_nop 0
	s_nop 0
	v_pk_mul_f32 v[240:241], v[54:55], s[98:99] op_sel_hi:[1,0]
	v_pk_mul_f32 v[234:235], v[54:55], s[98:99] op_sel:[0,1] op_sel_hi:[1,1]
	v_exp_f32_e32 v234, v234
	v_exp_f32_e32 v235, v235
	s_nop 0
	v_pk_add_f32 v[234:235], v[234:235], s[100:101] op_sel_hi:[1,0]
	v_rcp_f32_e32 v234, v234
	v_rcp_f32_e32 v235, v235
	s_nop 0
	v_pk_mul_f32 v[240:241], v[240:241], v[234:235]
	v_pk_mul_f32 v[240:241], v[240:241], v[50:51]
	s_nop 0
	s_nop 0
	s_nop 0
	s_nop 0
	v_pk_mul_f32 v[242:243], v[56:57], s[98:99] op_sel_hi:[1,0]
	v_pk_mul_f32 v[234:235], v[56:57], s[98:99] op_sel:[0,1] op_sel_hi:[1,1]
	v_exp_f32_e32 v234, v234
	v_exp_f32_e32 v235, v235
	s_nop 0
	v_pk_add_f32 v[234:235], v[234:235], s[100:101] op_sel_hi:[1,0]
	v_rcp_f32_e32 v234, v234
	v_rcp_f32_e32 v235, v235
	s_nop 0
	v_pk_mul_f32 v[242:243], v[242:243], v[234:235]
	v_pk_mul_f32 v[242:243], v[242:243], v[52:53]
	s_nop 0
	s_nop 0
	s_nop 0
	s_nop 0
	v_mov_b32_e32 v8, v163
	v_cvt_pk_fp8_f32 v8, v5, v7
	v_med3_f32 v5, v238, s40, v189
	v_med3_f32 v7, v239, s40, v189
	v_mov_b32_e32 v9, v163
	v_cvt_pk_fp8_f32 v8, v5, v7 op_sel:[0,0,1]
	v_med3_f32 v5, v240, s40, v189
	v_med3_f32 v7, v241, s40, v189
	v_cvt_pk_fp8_f32 v9, v5, v7
	v_add_u32_e32 v6, 0xa0, v4
	v_med3_f32 v5, v242, s40, v189
	v_med3_f32 v7, v243, s40, v189
	v_cvt_pk_fp8_f32 v9, v5, v7 op_sel:[0,0,1]
	v_ashrrev_i32_e32 v7, 31, v6
	v_lshlrev_b64 v[6:7], 7, v[6:7]
	v_lshl_add_u64 v[6:7], s[10:11], 0, v[6:7]
	v_lshl_add_u64 v[6:7], v[6:7], 0, v[2:3]
	v_pk_mul_f32 v[244:245], v[46:47], s[98:99] op_sel_hi:[1,0]
	v_pk_mul_f32 v[234:235], v[46:47], s[98:99] op_sel:[0,1] op_sel_hi:[1,1]
	v_exp_f32_e32 v234, v234
	v_exp_f32_e32 v235, v235
	s_nop 0
	v_pk_add_f32 v[234:235], v[234:235], s[100:101] op_sel_hi:[1,0]
	v_rcp_f32_e32 v234, v234
	v_rcp_f32_e32 v235, v235
	s_nop 0
	v_pk_mul_f32 v[244:245], v[244:245], v[234:235]
	v_pk_mul_f32 v[244:245], v[244:245], v[42:43]
	global_store_dwordx2 v[6:7], v[8:9], off
	v_add_u32_e32 v4, 0xb0, v4
	s_nop 0
	v_med3_f32 v5, v244, s40, v189
	s_nop 0
	v_pk_mul_f32 v[246:247], v[48:49], s[98:99] op_sel_hi:[1,0]
	v_pk_mul_f32 v[234:235], v[48:49], s[98:99] op_sel:[0,1] op_sel_hi:[1,1]
	v_exp_f32_e32 v234, v234
	v_exp_f32_e32 v235, v235
	s_nop 0
	v_pk_add_f32 v[234:235], v[234:235], s[100:101] op_sel_hi:[1,0]
	v_rcp_f32_e32 v234, v234
	v_rcp_f32_e32 v235, v235
	s_nop 0
	v_pk_mul_f32 v[246:247], v[246:247], v[234:235]
	v_pk_mul_f32 v[246:247], v[246:247], v[44:45]
	s_nop 0
	s_nop 0
	v_pk_mul_f32 v[248:249], v[38:39], s[98:99] op_sel_hi:[1,0]
	v_pk_mul_f32 v[234:235], v[38:39], s[98:99] op_sel:[0,1] op_sel_hi:[1,1]
	v_exp_f32_e32 v234, v234
	v_exp_f32_e32 v235, v235
	s_nop 0
	v_pk_add_f32 v[234:235], v[234:235], s[100:101] op_sel_hi:[1,0]
	v_rcp_f32_e32 v234, v234
	v_rcp_f32_e32 v235, v235
	s_nop 0
	v_pk_mul_f32 v[248:249], v[248:249], v[234:235]
	v_pk_mul_f32 v[248:249], v[248:249], v[34:35]
	s_nop 0
	s_nop 0
	v_pk_mul_f32 v[250:251], v[40:41], s[98:99] op_sel_hi:[1,0]
	v_pk_mul_f32 v[234:235], v[40:41], s[98:99] op_sel:[0,1] op_sel_hi:[1,1]
	v_exp_f32_e32 v234, v234
	v_exp_f32_e32 v235, v235
	s_nop 0
	v_pk_add_f32 v[234:235], v[234:235], s[100:101] op_sel_hi:[1,0]
	v_rcp_f32_e32 v234, v234
	v_rcp_f32_e32 v235, v235
	s_nop 0
	v_pk_mul_f32 v[250:251], v[250:251], v[234:235]
	v_pk_mul_f32 v[250:251], v[250:251], v[36:37]
	s_nop 0
	s_nop 0
	v_med3_f32 v13, v245, s40, v189
	v_mov_b32_e32 v6, v163
	v_cvt_pk_fp8_f32 v6, v5, v13
	v_med3_f32 v5, v246, s40, v189
	v_med3_f32 v7, v247, s40, v189
	v_med3_f32 v8, v249, s40, v189
	v_cvt_pk_fp8_f32 v6, v5, v7 op_sel:[0,0,1]
	v_med3_f32 v5, v248, s40, v189
	v_mov_b32_e32 v7, v163
	v_cvt_pk_fp8_f32 v7, v5, v8
	v_med3_f32 v5, v250, s40, v189
	v_med3_f32 v8, v251, s40, v189
	v_cvt_pk_fp8_f32 v7, v5, v8 op_sel:[0,0,1]
	v_ashrrev_i32_e32 v5, 31, v4
	v_lshlrev_b64 v[4:5], 7, v[4:5]
	v_lshl_add_u64 v[4:5], s[10:11], 0, v[4:5]
	v_lshl_add_u64 v[2:3], v[4:5], 0, v[2:3]
	global_store_dwordx2 v[2:3], v[6:7], off
	s_cbranch_vccz .LBB0_2738
	s_waitcnt vmcnt(0)
	s_cmpk_gt_u32 s42, 0xff
	s_cbranch_scc1 .LBB0_2684
	s_barrier
	s_branch .LBB0_2684
